# v11: v8 + P11 last epilogue deferred and interleaved into the next tile first MFMA chain (flag s98, flush at loop exits)
# speedup vs baseline: 1.0005x; 1.0002x over previous
; #define LAS __attribute__((address_space(3)))
; DI void indexer_tile(const LAS unsigned char* buf, const f16x8 (&af)[2][8], const f32x4 (&wv)[2][4], float* sc0, float* sc1, int kt, int r32, int h2) {
;     ...
;     f16x8 bfr[2][8];
; #pragma unroll
;     for (int sub = 0; sub < 2; ++sub)
; #pragma unroll
;         for (int ks = 0; ks < 8; ++ks) bfr[sub][ks] = *(const LAS f16x8*)(buf + (32 * sub + r32) * KT_ROWB + (16 * ks + 8 * h2) * 2);
;     __builtin_amdgcn_sched_barrier(0);
; #pragma unroll
;     for (int sub = 0; sub < 2; ++sub) {
;         f32x16 c0, c1;
; #pragma unroll
;         for (int i = 0; i < 16; ++i) { c0[i] = 0.f; c1[i] = 0.f; }
; #pragma unroll
;         for (int ks = 0; ks < 8; ++ks) { c0 = __builtin_amdgcn_mfma_f32_32x32x16_f16(af[0][ks], bfr[sub][ks], c0, 0, 0, 0); c1 = __builtin_amdgcn_mfma_f32_32x32x16_f16(af[1][ks], bfr[sub][ks], c1, 0, 0, 0); }
;         f32x2_t a0 = {0.f, 0.f}, a1 = {0.f, 0.f};
; #pragma unroll
;         for (int q = 0; q < 4; ++q)
; #pragma unroll
;             for (int e = 0; e < 4; e += 2) {
;                 const f32x2_t r0 = {relu1(c0[4 * q + e]), relu1(c0[4 * q + e + 1])};
;                 const f32x2_t r1 = {relu1(c1[4 * q + e]), relu1(c1[4 * q + e + 1])};
;                 const f32x2_t w0 = {wv[0][q][e], wv[0][q][e + 1]}, w1 = {wv[1][q][e], wv[1][q][e + 1]};
;                 a0 = __builtin_elementwise_fma(r0, w0, a0); a1 = __builtin_elementwise_fma(r1, w1, a1); }
;         float s0 = a0.x + a0.y, s1 = a1.x + a1.y;
;         s0 += __shfl_xor(s0, 32); s1 += __shfl_xor(s1, 32);
;         if (h2 == 0) { sc0[kt * 64 + 32 * sub + r32] = s0; sc1[kt * 64 + 32 * sub + r32] = s1; }
;     }
; DI void indexer_phase(const unsigned short* QI, const unsigned short* KI16, const float* WI, float* SC, LAS unsigned char* lds, int tid, int bid, int G) {
;     ...
;             for (int kt = 0; kt < nt; kt += 2) {
;                 if (kt + 2 < nt) { const unsigned short* p = src + (size_t)(kt + 2) * 64 * 128; a0 = *(const u32x4*)p; a1 = *(const u32x4*)(p + 32 * 128); }
;                 indexer_tile(buf0, af, wv, sc0, sc1, kt, r32, h2);
.LBB0_1827:
	ds_read_b128 v[250:253], v207
	ds_read_b128 v[210:213], v207 offset:32
	ds_read_b128 v[214:217], v207 offset:64
	ds_read_b128 v[218:221], v207 offset:96
	ds_read_b128 v[222:225], v207 offset:128
	ds_read_b128 v[226:229], v207 offset:160
	ds_read_b128 v[230:233], v207 offset:192
	ds_read_b128 v[234:237], v207 offset:224
	ds_read_b128 v[176:179], v207 offset:8704
	ds_read_b128 v[172:175], v207 offset:8736
	ds_read_b128 v[168:171], v207 offset:8768
	ds_read_b128 v[164:167], v207 offset:8800
	ds_read_b128 v[160:163], v207 offset:8832
	ds_read_b128 v[156:159], v207 offset:8864
	ds_read_b128 v[152:155], v207 offset:8896
	ds_read_b128 v[148:151], v207 offset:8928
	s_cmp_eq_u32 s98, 0
	s_cbranch_scc1 .Lp11_plain0
	s_waitcnt lgkmcnt(15)
	v_mfma_f32_32x32x16_f16 v[16:31], v[36:39], v[250:253], 0
	v_max_i32_e32 v0, 0, v0
	v_max_i32_e32 v1, 0, v1
	v_fma_f32 v243, v0, v116, 0
	v_fma_f32 v244, v1, v117, 0
	v_max_i32_e32 v2, 0, v2
	v_max_i32_e32 v3, 0, v3
	s_waitcnt lgkmcnt(14)
	v_mfma_f32_32x32x16_f16 v[16:31], v[40:43], v[210:213], v[16:31]
	v_fma_f32 v243, v2, v118, v243
	v_fma_f32 v244, v3, v119, v244
	v_max_i32_e32 v4, 0, v4
	v_max_i32_e32 v5, 0, v5
	v_fma_f32 v243, v4, v120, v243
	v_fma_f32 v244, v5, v121, v244
	s_waitcnt lgkmcnt(13)
	v_mfma_f32_32x32x16_f16 v[16:31], v[44:47], v[214:217], v[16:31]
	v_max_i32_e32 v6, 0, v6
	v_max_i32_e32 v7, 0, v7
	v_fma_f32 v243, v6, v122, v243
	v_fma_f32 v244, v7, v123, v244
	v_max_i32_e32 v8, 0, v8
	s_waitcnt lgkmcnt(12)
	v_mfma_f32_32x32x16_f16 v[16:31], v[48:51], v[218:221], v[16:31]
	v_max_i32_e32 v9, 0, v9
	v_fma_f32 v243, v8, v124, v243
	v_fma_f32 v244, v9, v125, v244
	v_max_i32_e32 v10, 0, v10
	v_max_i32_e32 v11, 0, v11
	s_waitcnt lgkmcnt(11)
	v_mfma_f32_32x32x16_f16 v[16:31], v[52:55], v[222:225], v[16:31]
	v_fma_f32 v243, v10, v126, v243
	v_fma_f32 v244, v11, v127, v244
	v_max_i32_e32 v12, 0, v12
	v_max_i32_e32 v13, 0, v13
	v_fma_f32 v243, v12, v128, v243
	s_waitcnt lgkmcnt(10)
	v_mfma_f32_32x32x16_f16 v[16:31], v[56:59], v[226:229], v[16:31]
	v_fma_f32 v244, v13, v129, v244
	v_max_i32_e32 v14, 0, v14
	v_max_i32_e32 v15, 0, v15
	v_fma_f32 v243, v14, v130, v243
	v_fma_f32 v244, v15, v131, v244
	s_waitcnt lgkmcnt(9)
	v_mfma_f32_32x32x16_f16 v[16:31], v[60:63], v[230:233], v[16:31]
	v_add_f32_e32 v245, v243, v244
	v_mov_b32_e32 v246, v245
	v_lshlrev_b32_e32 v247, 2, v32
	s_nop 0
	v_permlane32_swap_b32_e32 v246, v245
	s_waitcnt lgkmcnt(8)
	v_mfma_f32_32x32x16_f16 v[16:31], v[64:67], v[234:237], v[16:31]
	v_add_f32_e32 v246, v246, v245
	s_mov_b64 exec, s[4:5]
	global_store_dword v247, v246, s[20:21] offset:-128
	s_mov_b64 exec, -1
	s_branch .Lp11_join0

; #define LAS __attribute__((address_space(3)))
; DI void indexer_tile(const LAS unsigned char* buf, const f16x8 (&af)[2][8], const f32x4 (&wv)[2][4], float* sc0, float* sc1, int kt, int r32, int h2) {
;     ...
;     f16x8 bfr[2][8];
; #pragma unroll
;     for (int sub = 0; sub < 2; ++sub)
; #pragma unroll
;         for (int ks = 0; ks < 8; ++ks) bfr[sub][ks] = *(const LAS f16x8*)(buf + (32 * sub + r32) * KT_ROWB + (16 * ks + 8 * h2) * 2);
;     __builtin_amdgcn_sched_barrier(0);
; #pragma unroll
;     for (int sub = 0; sub < 2; ++sub) {
;         f32x16 c0, c1;
; #pragma unroll
;         for (int i = 0; i < 16; ++i) { c0[i] = 0.f; c1[i] = 0.f; }
; #pragma unroll
;         for (int ks = 0; ks < 8; ++ks) { c0 = __builtin_amdgcn_mfma_f32_32x32x16_f16(af[0][ks], bfr[sub][ks], c0, 0, 0, 0); c1 = __builtin_amdgcn_mfma_f32_32x32x16_f16(af[1][ks], bfr[sub][ks], c1, 0, 0, 0); }
;         f32x2_t a0 = {0.f, 0.f}, a1 = {0.f, 0.f};
; #pragma unroll
;         for (int q = 0; q < 4; ++q)
; #pragma unroll
;             for (int e = 0; e < 4; e += 2) {
;                 const f32x2_t r0 = {relu1(c0[4 * q + e]), relu1(c0[4 * q + e + 1])};
;                 const f32x2_t r1 = {relu1(c1[4 * q + e]), relu1(c1[4 * q + e + 1])};
;                 const f32x2_t w0 = {wv[0][q][e], wv[0][q][e + 1]}, w1 = {wv[1][q][e], wv[1][q][e + 1]};
;                 a0 = __builtin_elementwise_fma(r0, w0, a0); a1 = __builtin_elementwise_fma(r1, w1, a1); }
;         float s0 = a0.x + a0.y, s1 = a1.x + a1.y;
;         s0 += __shfl_xor(s0, 32); s1 += __shfl_xor(s1, 32);
;         if (h2 == 0) { sc0[kt * 64 + 32 * sub + r32] = s0; sc1[kt * 64 + 32 * sub + r32] = s1; }
;     }
; DI void indexer_phase(const unsigned short* QI, const unsigned short* KI16, const float* WI, float* SC, LAS unsigned char* lds, int tid, int bid, int G) {
;     ...
;                 indexer_tile(buf0, af, wv, sc0, sc1, kt, r32, h2);
;                 if (kt + 1 < nt) { *(LAS u32x4*)(buf1 + key0 * KT_ROWB + ch * 16) = b0; *(LAS u32x4*)(buf1 + (key0 + 32) * KT_ROWB + ch * 16) = b1; }
.Lp11_join0:
	v_mfma_f32_32x32x16_f16 v[0:15], v[84:87], v[250:253], 0
	v_mfma_f32_32x32x16_f16 v[0:15], v[88:91], v[210:213], v[0:15]
	v_mfma_f32_32x32x16_f16 v[0:15], v[92:95], v[214:217], v[0:15]
	s_nop 8
	v_max_i32_e32 v16, 0, v16
	v_max_i32_e32 v17, 0, v17
	v_fma_f32 v238, v16, v68, 0
	v_fma_f32 v239, v17, v69, 0
	v_max_i32_e32 v18, 0, v18
	v_max_i32_e32 v19, 0, v19
	v_fma_f32 v238, v18, v70, v238
	v_mfma_f32_32x32x16_f16 v[0:15], v[96:99], v[218:221], v[0:15]
	v_fma_f32 v239, v19, v71, v239
	v_max_i32_e32 v20, 0, v20
	v_max_i32_e32 v21, 0, v21
	v_fma_f32 v238, v20, v72, v238
	v_fma_f32 v239, v21, v73, v239
	v_max_i32_e32 v22, 0, v22
	v_max_i32_e32 v23, 0, v23
	v_mfma_f32_32x32x16_f16 v[0:15], v[100:103], v[222:225], v[0:15]
	v_fma_f32 v238, v22, v74, v238
	v_fma_f32 v239, v23, v75, v239
	v_max_i32_e32 v24, 0, v24
	v_max_i32_e32 v25, 0, v25
	v_fma_f32 v238, v24, v76, v238
	v_fma_f32 v239, v25, v77, v239
	v_mfma_f32_32x32x16_f16 v[0:15], v[104:107], v[226:229], v[0:15]
	v_max_i32_e32 v26, 0, v26
	v_max_i32_e32 v27, 0, v27
	v_fma_f32 v238, v26, v78, v238
	v_fma_f32 v239, v27, v79, v239
	v_max_i32_e32 v28, 0, v28
	v_max_i32_e32 v29, 0, v29
	v_mfma_f32_32x32x16_f16 v[0:15], v[108:111], v[230:233], v[0:15]
	v_fma_f32 v238, v28, v80, v238
	v_fma_f32 v239, v29, v81, v239
	v_max_i32_e32 v30, 0, v30
	v_max_i32_e32 v31, 0, v31
	v_fma_f32 v238, v30, v82, v238
	v_fma_f32 v239, v31, v83, v239
	v_mfma_f32_32x32x16_f16 v[0:15], v[112:115], v[234:237], v[0:15]
	v_add_f32_e32 v240, v238, v239
	v_mov_b32_e32 v241, v240
	v_lshlrev_b32_e32 v242, 2, v32
	s_nop 0
	v_permlane32_swap_b32_e32 v241, v240
	v_add_f32_e32 v241, v241, v240
	s_mov_b64 exec, s[4:5]
	global_store_dword v242, v241, s[18:19]
	s_mov_b64 exec, -1
	s_waitcnt lgkmcnt(0)
	v_mfma_f32_32x32x16_f16 v[16:31], v[36:39], v[176:179], 0
	v_mfma_f32_32x32x16_f16 v[16:31], v[40:43], v[172:175], v[16:31]
	v_mfma_f32_32x32x16_f16 v[16:31], v[44:47], v[168:171], v[16:31]
	s_nop 8
	v_max_i32_e32 v0, 0, v0
	v_max_i32_e32 v1, 0, v1
	v_fma_f32 v243, v0, v116, 0
	v_fma_f32 v244, v1, v117, 0
	v_max_i32_e32 v2, 0, v2
	v_max_i32_e32 v3, 0, v3
	v_fma_f32 v243, v2, v118, v243
	v_mfma_f32_32x32x16_f16 v[16:31], v[48:51], v[164:167], v[16:31]
	v_fma_f32 v244, v3, v119, v244
	v_max_i32_e32 v4, 0, v4
	v_max_i32_e32 v5, 0, v5
	v_fma_f32 v243, v4, v120, v243
	v_fma_f32 v244, v5, v121, v244
	v_max_i32_e32 v6, 0, v6
	v_max_i32_e32 v7, 0, v7
	v_mfma_f32_32x32x16_f16 v[16:31], v[52:55], v[160:163], v[16:31]
	v_fma_f32 v243, v6, v122, v243
	v_fma_f32 v244, v7, v123, v244
	v_max_i32_e32 v8, 0, v8
	v_max_i32_e32 v9, 0, v9
	v_fma_f32 v243, v8, v124, v243
	v_fma_f32 v244, v9, v125, v244
	v_mfma_f32_32x32x16_f16 v[16:31], v[56:59], v[156:159], v[16:31]
	v_max_i32_e32 v10, 0, v10
	v_max_i32_e32 v11, 0, v11
	v_fma_f32 v243, v10, v126, v243
	v_fma_f32 v244, v11, v127, v244
	v_max_i32_e32 v12, 0, v12
	v_max_i32_e32 v13, 0, v13
	v_mfma_f32_32x32x16_f16 v[16:31], v[60:63], v[152:155], v[16:31]
	v_fma_f32 v243, v12, v128, v243
	v_fma_f32 v244, v13, v129, v244
	v_max_i32_e32 v14, 0, v14
	v_max_i32_e32 v15, 0, v15
	v_fma_f32 v243, v14, v130, v243
	v_fma_f32 v244, v15, v131, v244
	v_mfma_f32_32x32x16_f16 v[16:31], v[64:67], v[148:151], v[16:31]
	v_add_f32_e32 v245, v243, v244
	v_mov_b32_e32 v246, v245
	v_lshlrev_b32_e32 v247, 2, v32
	s_nop 0
	v_permlane32_swap_b32_e32 v246, v245
	v_add_f32_e32 v246, v246, v245
	s_mov_b64 exec, s[4:5]
	global_store_dword v247, v246, s[20:21]
	s_mov_b64 exec, -1
	v_mfma_f32_32x32x16_f16 v[0:15], v[84:87], v[176:179], 0
	v_mfma_f32_32x32x16_f16 v[0:15], v[88:91], v[172:175], v[0:15]
	v_mfma_f32_32x32x16_f16 v[0:15], v[92:95], v[168:171], v[0:15]
	s_nop 8
	v_max_i32_e32 v16, 0, v16
	v_max_i32_e32 v17, 0, v17
	v_fma_f32 v238, v16, v68, 0
	v_fma_f32 v239, v17, v69, 0
	v_max_i32_e32 v18, 0, v18
	v_max_i32_e32 v19, 0, v19
	v_fma_f32 v238, v18, v70, v238
	v_mfma_f32_32x32x16_f16 v[0:15], v[96:99], v[164:167], v[0:15]
	v_fma_f32 v239, v19, v71, v239
	v_max_i32_e32 v20, 0, v20
	v_max_i32_e32 v21, 0, v21
	v_fma_f32 v238, v20, v72, v238
	v_fma_f32 v239, v21, v73, v239
	v_max_i32_e32 v22, 0, v22
	v_max_i32_e32 v23, 0, v23
	v_mfma_f32_32x32x16_f16 v[0:15], v[100:103], v[160:163], v[0:15]
	v_fma_f32 v238, v22, v74, v238
	v_fma_f32 v239, v23, v75, v239
	v_max_i32_e32 v24, 0, v24
	v_max_i32_e32 v25, 0, v25
	v_fma_f32 v238, v24, v76, v238
	v_fma_f32 v239, v25, v77, v239
	v_mfma_f32_32x32x16_f16 v[0:15], v[104:107], v[156:159], v[0:15]
	v_max_i32_e32 v26, 0, v26
	v_max_i32_e32 v27, 0, v27
	v_fma_f32 v238, v26, v78, v238
	v_fma_f32 v239, v27, v79, v239
	v_max_i32_e32 v28, 0, v28
	v_max_i32_e32 v29, 0, v29
	v_mfma_f32_32x32x16_f16 v[0:15], v[108:111], v[152:155], v[0:15]
	v_fma_f32 v238, v28, v80, v238
	v_fma_f32 v239, v29, v81, v239
	v_max_i32_e32 v30, 0, v30
	v_max_i32_e32 v31, 0, v31
	v_fma_f32 v238, v30, v82, v238
	v_fma_f32 v239, v31, v83, v239
	v_mfma_f32_32x32x16_f16 v[0:15], v[112:115], v[148:151], v[0:15]
	v_add_f32_e32 v240, v238, v239
	v_mov_b32_e32 v241, v240
	v_lshlrev_b32_e32 v242, 2, v32
	s_nop 0
	v_permlane32_swap_b32_e32 v241, v240
	v_add_f32_e32 v241, v241, v240
	s_mov_b64 exec, s[4:5]
	global_store_dword v242, v241, s[18:19] offset:128
	s_mov_b64 exec, -1
	s_mov_b32 s98, 1
	s_add_i32 s27, s11, -3
	s_cmp_lt_i32 s27, s41
	s_cselect_b64 s[24:25], -1, 0
	s_cmp_ge_i32 s27, s41
	s_cbranch_scc1 .LBB0_1833
	s_waitcnt vmcnt(8)
	ds_write_b128 v209, v[140:143] offset:17408
	ds_write_b128 v209, v[144:147] offset:26112

; #define LAS __attribute__((address_space(3)))
; DI void indexer_tile(const LAS unsigned char* buf, const f16x8 (&af)[2][8], const f32x4 (&wv)[2][4], float* sc0, float* sc1, int kt, int r32, int h2) {
;     ...
;     f16x8 bfr[2][8];
; #pragma unroll
;     for (int sub = 0; sub < 2; ++sub)
; #pragma unroll
;         for (int ks = 0; ks < 8; ++ks) bfr[sub][ks] = *(const LAS f16x8*)(buf + (32 * sub + r32) * KT_ROWB + (16 * ks + 8 * h2) * 2);
;     __builtin_amdgcn_sched_barrier(0);
; #pragma unroll
;     for (int sub = 0; sub < 2; ++sub) {
;         f32x16 c0, c1;
; #pragma unroll
;         for (int i = 0; i < 16; ++i) { c0[i] = 0.f; c1[i] = 0.f; }
; #pragma unroll
;         for (int ks = 0; ks < 8; ++ks) { c0 = __builtin_amdgcn_mfma_f32_32x32x16_f16(af[0][ks], bfr[sub][ks], c0, 0, 0, 0); c1 = __builtin_amdgcn_mfma_f32_32x32x16_f16(af[1][ks], bfr[sub][ks], c1, 0, 0, 0); }
;         f32x2_t a0 = {0.f, 0.f}, a1 = {0.f, 0.f};
; #pragma unroll
;         for (int q = 0; q < 4; ++q)
; #pragma unroll
;             for (int e = 0; e < 4; e += 2) {
;                 const f32x2_t r0 = {relu1(c0[4 * q + e]), relu1(c0[4 * q + e + 1])};
;                 const f32x2_t r1 = {relu1(c1[4 * q + e]), relu1(c1[4 * q + e + 1])};
;                 const f32x2_t w0 = {wv[0][q][e], wv[0][q][e + 1]}, w1 = {wv[1][q][e], wv[1][q][e + 1]};
;                 a0 = __builtin_elementwise_fma(r0, w0, a0); a1 = __builtin_elementwise_fma(r1, w1, a1); }
;         float s0 = a0.x + a0.y, s1 = a1.x + a1.y;
;         s0 += __shfl_xor(s0, 32); s1 += __shfl_xor(s1, 32);
;         if (h2 == 0) { sc0[kt * 64 + 32 * sub + r32] = s0; sc1[kt * 64 + 32 * sub + r32] = s1; }
;     }
; DI void indexer_phase(const unsigned short* QI, const unsigned short* KI16, const float* WI, float* SC, LAS unsigned char* lds, int tid, int bid, int G) {
;     ...
;                 if (kt + 3 < nt) { const unsigned short* p = src + (size_t)(kt + 3) * 64 * 128; b0 = *(const u32x4*)p; b1 = *(const u32x4*)(p + 32 * 128); }
;                 indexer_tile(buf1, af, wv, sc0, sc1, kt + 1, r32, h2);
.LBB0_1836:
	ds_read_b128 v[250:253], v207 offset:17408
	ds_read_b128 v[210:213], v207 offset:17440
	ds_read_b128 v[214:217], v207 offset:17472
	ds_read_b128 v[218:221], v207 offset:17504
	ds_read_b128 v[222:225], v207 offset:17536
	ds_read_b128 v[226:229], v207 offset:17568
	ds_read_b128 v[230:233], v207 offset:17600
	ds_read_b128 v[234:237], v207 offset:17632
	ds_read_b128 v[176:179], v207 offset:26112
	ds_read_b128 v[172:175], v207 offset:26144
	ds_read_b128 v[168:171], v207 offset:26176
	ds_read_b128 v[164:167], v207 offset:26208
	ds_read_b128 v[160:163], v207 offset:26240
	ds_read_b128 v[156:159], v207 offset:26272
	ds_read_b128 v[152:155], v207 offset:26304
	ds_read_b128 v[148:151], v207 offset:26336
	s_cmp_eq_u32 s98, 0
	s_cbranch_scc1 .Lp11_plain1
	s_waitcnt lgkmcnt(15)
	v_mfma_f32_32x32x16_f16 v[16:31], v[36:39], v[250:253], 0
	v_max_i32_e32 v0, 0, v0
	v_max_i32_e32 v1, 0, v1
	v_fma_f32 v243, v0, v116, 0
	v_fma_f32 v244, v1, v117, 0
	v_max_i32_e32 v2, 0, v2
	v_max_i32_e32 v3, 0, v3
	s_waitcnt lgkmcnt(14)
	v_mfma_f32_32x32x16_f16 v[16:31], v[40:43], v[210:213], v[16:31]
	v_fma_f32 v243, v2, v118, v243
	v_fma_f32 v244, v3, v119, v244
	v_max_i32_e32 v4, 0, v4
	v_max_i32_e32 v5, 0, v5
	v_fma_f32 v243, v4, v120, v243
	v_fma_f32 v244, v5, v121, v244
	s_waitcnt lgkmcnt(13)
	v_mfma_f32_32x32x16_f16 v[16:31], v[44:47], v[214:217], v[16:31]
	v_max_i32_e32 v6, 0, v6
	v_max_i32_e32 v7, 0, v7
	v_fma_f32 v243, v6, v122, v243
	v_fma_f32 v244, v7, v123, v244
	v_max_i32_e32 v8, 0, v8
	s_waitcnt lgkmcnt(12)
	v_mfma_f32_32x32x16_f16 v[16:31], v[48:51], v[218:221], v[16:31]
	v_max_i32_e32 v9, 0, v9
	v_fma_f32 v243, v8, v124, v243
	v_fma_f32 v244, v9, v125, v244
	v_max_i32_e32 v10, 0, v10
	v_max_i32_e32 v11, 0, v11
	s_waitcnt lgkmcnt(11)
	v_mfma_f32_32x32x16_f16 v[16:31], v[52:55], v[222:225], v[16:31]
	v_fma_f32 v243, v10, v126, v243
	v_fma_f32 v244, v11, v127, v244
	v_max_i32_e32 v12, 0, v12
	v_max_i32_e32 v13, 0, v13
	v_fma_f32 v243, v12, v128, v243
	s_waitcnt lgkmcnt(10)
	v_mfma_f32_32x32x16_f16 v[16:31], v[56:59], v[226:229], v[16:31]
	v_fma_f32 v244, v13, v129, v244
	v_max_i32_e32 v14, 0, v14
	v_max_i32_e32 v15, 0, v15
	v_fma_f32 v243, v14, v130, v243
	v_fma_f32 v244, v15, v131, v244
	s_waitcnt lgkmcnt(9)
	v_mfma_f32_32x32x16_f16 v[16:31], v[60:63], v[230:233], v[16:31]
	v_add_f32_e32 v245, v243, v244
	v_mov_b32_e32 v246, v245
	v_lshlrev_b32_e32 v247, 2, v32
	s_nop 0
	v_permlane32_swap_b32_e32 v246, v245
	s_waitcnt lgkmcnt(8)
	v_mfma_f32_32x32x16_f16 v[16:31], v[64:67], v[234:237], v[16:31]
	v_add_f32_e32 v246, v246, v245
	s_mov_b64 exec, s[4:5]
	global_store_dword v247, v246, s[20:21] offset:128
	s_mov_b64 exec, -1
	s_branch .Lp11_join1

; #define LAS __attribute__((address_space(3)))
; DI void indexer_tile(const LAS unsigned char* buf, const f16x8 (&af)[2][8], const f32x4 (&wv)[2][4], float* sc0, float* sc1, int kt, int r32, int h2) {
;     ...
;     f16x8 bfr[2][8];
; #pragma unroll
;     for (int sub = 0; sub < 2; ++sub)
; #pragma unroll
;         for (int ks = 0; ks < 8; ++ks) bfr[sub][ks] = *(const LAS f16x8*)(buf + (32 * sub + r32) * KT_ROWB + (16 * ks + 8 * h2) * 2);
;     __builtin_amdgcn_sched_barrier(0);
; #pragma unroll
;     for (int sub = 0; sub < 2; ++sub) {
;         f32x16 c0, c1;
; #pragma unroll
;         for (int i = 0; i < 16; ++i) { c0[i] = 0.f; c1[i] = 0.f; }
; #pragma unroll
;         for (int ks = 0; ks < 8; ++ks) { c0 = __builtin_amdgcn_mfma_f32_32x32x16_f16(af[0][ks], bfr[sub][ks], c0, 0, 0, 0); c1 = __builtin_amdgcn_mfma_f32_32x32x16_f16(af[1][ks], bfr[sub][ks], c1, 0, 0, 0); }
;         f32x2_t a0 = {0.f, 0.f}, a1 = {0.f, 0.f};
; #pragma unroll
;         for (int q = 0; q < 4; ++q)
; #pragma unroll
;             for (int e = 0; e < 4; e += 2) {
;                 const f32x2_t r0 = {relu1(c0[4 * q + e]), relu1(c0[4 * q + e + 1])};
;                 const f32x2_t r1 = {relu1(c1[4 * q + e]), relu1(c1[4 * q + e + 1])};
;                 const f32x2_t w0 = {wv[0][q][e], wv[0][q][e + 1]}, w1 = {wv[1][q][e], wv[1][q][e + 1]};
;                 a0 = __builtin_elementwise_fma(r0, w0, a0); a1 = __builtin_elementwise_fma(r1, w1, a1); }
;         float s0 = a0.x + a0.y, s1 = a1.x + a1.y;
;         s0 += __shfl_xor(s0, 32); s1 += __shfl_xor(s1, 32);
;         if (h2 == 0) { sc0[kt * 64 + 32 * sub + r32] = s0; sc1[kt * 64 + 32 * sub + r32] = s1; }
;     }
; DI void indexer_phase(const unsigned short* QI, const unsigned short* KI16, const float* WI, float* SC, LAS unsigned char* lds, int tid, int bid, int G) {
;     ...
;                 if (kt + 2 < nt) { *(LAS u32x4*)(buf0 + key0 * KT_ROWB + ch * 16) = a0; *(LAS u32x4*)(buf0 + (key0 + 32) * KT_ROWB + ch * 16) = a1; }
;                 __syncthreads();
.Lp11_join1:
	v_mfma_f32_32x32x16_f16 v[0:15], v[84:87], v[250:253], 0
	v_mfma_f32_32x32x16_f16 v[0:15], v[88:91], v[210:213], v[0:15]
	v_mfma_f32_32x32x16_f16 v[0:15], v[92:95], v[214:217], v[0:15]
	s_nop 8
	v_max_i32_e32 v16, 0, v16
	v_max_i32_e32 v17, 0, v17
	v_fma_f32 v238, v16, v68, 0
	v_fma_f32 v239, v17, v69, 0
	v_max_i32_e32 v18, 0, v18
	v_max_i32_e32 v19, 0, v19
	v_fma_f32 v238, v18, v70, v238
	v_mfma_f32_32x32x16_f16 v[0:15], v[96:99], v[218:221], v[0:15]
	v_fma_f32 v239, v19, v71, v239
	v_max_i32_e32 v20, 0, v20
	v_max_i32_e32 v21, 0, v21
	v_fma_f32 v238, v20, v72, v238
	v_fma_f32 v239, v21, v73, v239
	v_max_i32_e32 v22, 0, v22
	v_max_i32_e32 v23, 0, v23
	v_mfma_f32_32x32x16_f16 v[0:15], v[100:103], v[222:225], v[0:15]
	v_fma_f32 v238, v22, v74, v238
	v_fma_f32 v239, v23, v75, v239
	v_max_i32_e32 v24, 0, v24
	v_max_i32_e32 v25, 0, v25
	v_fma_f32 v238, v24, v76, v238
	v_fma_f32 v239, v25, v77, v239
	v_mfma_f32_32x32x16_f16 v[0:15], v[104:107], v[226:229], v[0:15]
	v_max_i32_e32 v26, 0, v26
	v_max_i32_e32 v27, 0, v27
	v_fma_f32 v238, v26, v78, v238
	v_fma_f32 v239, v27, v79, v239
	v_max_i32_e32 v28, 0, v28
	v_max_i32_e32 v29, 0, v29
	v_mfma_f32_32x32x16_f16 v[0:15], v[108:111], v[230:233], v[0:15]
	v_fma_f32 v238, v28, v80, v238
	v_fma_f32 v239, v29, v81, v239
	v_max_i32_e32 v30, 0, v30
	v_max_i32_e32 v31, 0, v31
	v_fma_f32 v238, v30, v82, v238
	v_fma_f32 v239, v31, v83, v239
	v_mfma_f32_32x32x16_f16 v[0:15], v[112:115], v[234:237], v[0:15]
	v_add_f32_e32 v240, v238, v239
	v_mov_b32_e32 v241, v240
	v_lshlrev_b32_e32 v242, 2, v32
	s_nop 0
	v_permlane32_swap_b32_e32 v241, v240
	v_add_f32_e32 v241, v241, v240
	s_mov_b64 exec, s[4:5]
	global_store_dword v242, v241, s[18:19] offset:256
	s_mov_b64 exec, -1
	s_waitcnt lgkmcnt(0)
	v_mfma_f32_32x32x16_f16 v[16:31], v[36:39], v[176:179], 0
	v_mfma_f32_32x32x16_f16 v[16:31], v[40:43], v[172:175], v[16:31]
	v_mfma_f32_32x32x16_f16 v[16:31], v[44:47], v[168:171], v[16:31]
	s_nop 8
	v_max_i32_e32 v0, 0, v0
	v_max_i32_e32 v1, 0, v1
	v_fma_f32 v243, v0, v116, 0
	v_fma_f32 v244, v1, v117, 0
	v_max_i32_e32 v2, 0, v2
	v_max_i32_e32 v3, 0, v3
	v_fma_f32 v243, v2, v118, v243
	v_mfma_f32_32x32x16_f16 v[16:31], v[48:51], v[164:167], v[16:31]
	v_fma_f32 v244, v3, v119, v244
	v_max_i32_e32 v4, 0, v4
	v_max_i32_e32 v5, 0, v5
	v_fma_f32 v243, v4, v120, v243
	v_fma_f32 v244, v5, v121, v244
	v_max_i32_e32 v6, 0, v6
	v_max_i32_e32 v7, 0, v7
	v_mfma_f32_32x32x16_f16 v[16:31], v[52:55], v[160:163], v[16:31]
	v_fma_f32 v243, v6, v122, v243
	v_fma_f32 v244, v7, v123, v244
	v_max_i32_e32 v8, 0, v8
	v_max_i32_e32 v9, 0, v9
	v_fma_f32 v243, v8, v124, v243
	v_fma_f32 v244, v9, v125, v244
	v_mfma_f32_32x32x16_f16 v[16:31], v[56:59], v[156:159], v[16:31]
	v_max_i32_e32 v10, 0, v10
	v_max_i32_e32 v11, 0, v11
	v_fma_f32 v243, v10, v126, v243
	v_fma_f32 v244, v11, v127, v244
	v_max_i32_e32 v12, 0, v12
	v_max_i32_e32 v13, 0, v13
	v_mfma_f32_32x32x16_f16 v[16:31], v[60:63], v[152:155], v[16:31]
	v_fma_f32 v243, v12, v128, v243
	v_fma_f32 v244, v13, v129, v244
	v_max_i32_e32 v14, 0, v14
	v_max_i32_e32 v15, 0, v15
	v_fma_f32 v243, v14, v130, v243
	v_fma_f32 v244, v15, v131, v244
	v_mfma_f32_32x32x16_f16 v[16:31], v[64:67], v[148:151], v[16:31]
	v_add_f32_e32 v245, v243, v244
	v_mov_b32_e32 v246, v245
	v_lshlrev_b32_e32 v247, 2, v32
	s_nop 0
	v_permlane32_swap_b32_e32 v246, v245
	v_add_f32_e32 v246, v246, v245
	s_mov_b64 exec, s[4:5]
	global_store_dword v247, v246, s[20:21] offset:256
	s_mov_b64 exec, -1
	v_mfma_f32_32x32x16_f16 v[0:15], v[84:87], v[176:179], 0
	v_mfma_f32_32x32x16_f16 v[0:15], v[88:91], v[172:175], v[0:15]
	v_mfma_f32_32x32x16_f16 v[0:15], v[92:95], v[168:171], v[0:15]
	s_nop 8
	v_max_i32_e32 v16, 0, v16
	v_max_i32_e32 v17, 0, v17
	v_fma_f32 v238, v16, v68, 0
	v_fma_f32 v239, v17, v69, 0
	v_max_i32_e32 v18, 0, v18
	v_max_i32_e32 v19, 0, v19
	v_fma_f32 v238, v18, v70, v238
	v_mfma_f32_32x32x16_f16 v[0:15], v[96:99], v[164:167], v[0:15]
	v_fma_f32 v239, v19, v71, v239
	v_max_i32_e32 v20, 0, v20
	v_max_i32_e32 v21, 0, v21
	v_fma_f32 v238, v20, v72, v238
	v_fma_f32 v239, v21, v73, v239
	v_max_i32_e32 v22, 0, v22
	v_max_i32_e32 v23, 0, v23
	v_mfma_f32_32x32x16_f16 v[0:15], v[100:103], v[160:163], v[0:15]
	v_fma_f32 v238, v22, v74, v238
	v_fma_f32 v239, v23, v75, v239
	v_max_i32_e32 v24, 0, v24
	v_max_i32_e32 v25, 0, v25
	v_fma_f32 v238, v24, v76, v238
	v_fma_f32 v239, v25, v77, v239
	v_mfma_f32_32x32x16_f16 v[0:15], v[104:107], v[156:159], v[0:15]
	v_max_i32_e32 v26, 0, v26
	v_max_i32_e32 v27, 0, v27
	v_fma_f32 v238, v26, v78, v238
	v_fma_f32 v239, v27, v79, v239
	v_max_i32_e32 v28, 0, v28
	v_max_i32_e32 v29, 0, v29
	v_mfma_f32_32x32x16_f16 v[0:15], v[108:111], v[152:155], v[0:15]
	v_fma_f32 v238, v28, v80, v238
	v_fma_f32 v239, v29, v81, v239
	v_max_i32_e32 v30, 0, v30
	v_max_i32_e32 v31, 0, v31
	v_fma_f32 v238, v30, v82, v238
	v_fma_f32 v239, v31, v83, v239
	v_mfma_f32_32x32x16_f16 v[0:15], v[112:115], v[148:151], v[0:15]
	v_add_f32_e32 v240, v238, v239
	v_mov_b32_e32 v241, v240
	v_lshlrev_b32_e32 v242, 2, v32
	s_nop 0
	v_permlane32_swap_b32_e32 v241, v240
	v_add_f32_e32 v241, v241, v240
	s_mov_b64 exec, s[4:5]
	global_store_dword v242, v241, s[18:19] offset:384
	s_mov_b64 exec, -1
	s_mov_b32 s98, 1
	s_andn2_b64 vcc, exec, s[22:23]
	s_cbranch_vccnz .LBB0_1824
	s_waitcnt vmcnt(7)
	ds_write_b128 v209, v[132:135]
	ds_write_b128 v209, v[136:139] offset:8704
	s_branch .LBB0_1824

; #define LAS __attribute__((address_space(3)))
; DI void indexer_tile(const LAS unsigned char* buf, const f16x8 (&af)[2][8], const f32x4 (&wv)[2][4], float* sc0, float* sc1, int kt, int r32, int h2) {
;     ...
;     f16x8 bfr[2][8];
; #pragma unroll
;     for (int sub = 0; sub < 2; ++sub)
; #pragma unroll
;         for (int ks = 0; ks < 8; ++ks) bfr[sub][ks] = *(const LAS f16x8*)(buf + (32 * sub + r32) * KT_ROWB + (16 * ks + 8 * h2) * 2);
;     __builtin_amdgcn_sched_barrier(0);
; #pragma unroll
;     for (int sub = 0; sub < 2; ++sub) {
;         f32x16 c0, c1;
; #pragma unroll
;         for (int i = 0; i < 16; ++i) { c0[i] = 0.f; c1[i] = 0.f; }
; #pragma unroll
;         for (int ks = 0; ks < 8; ++ks) { c0 = __builtin_amdgcn_mfma_f32_32x32x16_f16(af[0][ks], bfr[sub][ks], c0, 0, 0, 0); c1 = __builtin_amdgcn_mfma_f32_32x32x16_f16(af[1][ks], bfr[sub][ks], c1, 0, 0, 0); }
;         f32x2_t a0 = {0.f, 0.f}, a1 = {0.f, 0.f};
; #pragma unroll
;         for (int q = 0; q < 4; ++q)
; #pragma unroll
;             for (int e = 0; e < 4; e += 2) {
;                 const f32x2_t r0 = {relu1(c0[4 * q + e]), relu1(c0[4 * q + e + 1])};
;                 const f32x2_t r1 = {relu1(c1[4 * q + e]), relu1(c1[4 * q + e + 1])};
;                 const f32x2_t w0 = {wv[0][q][e], wv[0][q][e + 1]}, w1 = {wv[1][q][e], wv[1][q][e + 1]};
;                 a0 = __builtin_elementwise_fma(r0, w0, a0); a1 = __builtin_elementwise_fma(r1, w1, a1); }
;         float s0 = a0.x + a0.y, s1 = a1.x + a1.y;
;         s0 += __shfl_xor(s0, 32); s1 += __shfl_xor(s1, 32);
;         if (h2 == 0) { sc0[kt * 64 + 32 * sub + r32] = s0; sc1[kt * 64 + 32 * sub + r32] = s1; }
;     }
; DI void indexer_phase(const unsigned short* QI, const unsigned short* KI16, const float* WI, float* SC, LAS unsigned char* lds, int tid, int bid, int G) {
;     ...
;             for (int kt = 0; kt < nt; kt += 2) {
;                 if (kt + 2 < nt) { const unsigned short* p = src + (size_t)(kt + 2) * 64 * 128; a0 = *(const u32x4*)p; a1 = *(const u32x4*)(p + 32 * 128); }
;                 indexer_tile(buf0, af, wv, sc0, sc1, kt, r32, h2);
.LBB0_1847:
	ds_read_b128 v[250:253], v207
	ds_read_b128 v[210:213], v207 offset:32
	ds_read_b128 v[214:217], v207 offset:64
	ds_read_b128 v[218:221], v207 offset:96
	ds_read_b128 v[222:225], v207 offset:128
	ds_read_b128 v[226:229], v207 offset:160
	ds_read_b128 v[230:233], v207 offset:192
	ds_read_b128 v[234:237], v207 offset:224
	ds_read_b128 v[174:177], v207 offset:8704
	ds_read_b128 v[170:173], v207 offset:8736
	ds_read_b128 v[166:169], v207 offset:8768
	ds_read_b128 v[162:165], v207 offset:8800
	ds_read_b128 v[158:161], v207 offset:8832
	ds_read_b128 v[154:157], v207 offset:8864
	ds_read_b128 v[150:153], v207 offset:8896
	ds_read_b128 v[146:149], v207 offset:8928
	s_cmp_eq_u32 s98, 0
	s_cbranch_scc1 .Lp11_plain2
	s_waitcnt lgkmcnt(15)
	v_mfma_f32_32x32x16_f16 v[16:31], v[34:37], v[250:253], 0
	v_max_i32_e32 v0, 0, v0
	v_max_i32_e32 v1, 0, v1
	v_fma_f32 v243, v0, v114, 0
	v_fma_f32 v244, v1, v115, 0
	v_max_i32_e32 v2, 0, v2
	v_max_i32_e32 v3, 0, v3
	s_waitcnt lgkmcnt(14)
	v_mfma_f32_32x32x16_f16 v[16:31], v[38:41], v[210:213], v[16:31]
	v_fma_f32 v243, v2, v116, v243
	v_fma_f32 v244, v3, v117, v244
	v_max_i32_e32 v4, 0, v4
	v_max_i32_e32 v5, 0, v5
	v_fma_f32 v243, v4, v118, v243
	v_fma_f32 v244, v5, v119, v244
	s_waitcnt lgkmcnt(13)
	v_mfma_f32_32x32x16_f16 v[16:31], v[42:45], v[214:217], v[16:31]
	v_max_i32_e32 v6, 0, v6
	v_max_i32_e32 v7, 0, v7
	v_fma_f32 v243, v6, v120, v243
	v_fma_f32 v244, v7, v121, v244
	v_max_i32_e32 v8, 0, v8
	s_waitcnt lgkmcnt(12)
	v_mfma_f32_32x32x16_f16 v[16:31], v[46:49], v[218:221], v[16:31]
	v_max_i32_e32 v9, 0, v9
	v_fma_f32 v243, v8, v122, v243
	v_fma_f32 v244, v9, v123, v244
	v_max_i32_e32 v10, 0, v10
	v_max_i32_e32 v11, 0, v11
	s_waitcnt lgkmcnt(11)
	v_mfma_f32_32x32x16_f16 v[16:31], v[50:53], v[222:225], v[16:31]
	v_fma_f32 v243, v10, v124, v243
	v_fma_f32 v244, v11, v125, v244
	v_max_i32_e32 v12, 0, v12
	v_max_i32_e32 v13, 0, v13
	v_fma_f32 v243, v12, v126, v243
	s_waitcnt lgkmcnt(10)
	v_mfma_f32_32x32x16_f16 v[16:31], v[54:57], v[226:229], v[16:31]
	v_fma_f32 v244, v13, v127, v244
	v_max_i32_e32 v14, 0, v14
	v_max_i32_e32 v15, 0, v15
	v_fma_f32 v243, v14, v128, v243
	v_fma_f32 v244, v15, v129, v244
	s_waitcnt lgkmcnt(9)
	v_mfma_f32_32x32x16_f16 v[16:31], v[58:61], v[230:233], v[16:31]
	v_add_f32_e32 v245, v243, v244
	v_mov_b32_e32 v246, v245
	v_lshlrev_b32_e32 v247, 2, v32
	s_nop 0
	v_permlane32_swap_b32_e32 v246, v245
	s_waitcnt lgkmcnt(8)
	v_mfma_f32_32x32x16_f16 v[16:31], v[62:65], v[234:237], v[16:31]
	v_add_f32_e32 v246, v246, v245
	s_mov_b64 exec, s[4:5]
	global_store_dword v247, v246, s[26:27] offset:-128
	s_mov_b64 exec, -1
	s_branch .Lp11_join2

; #define LAS __attribute__((address_space(3)))
; DI void indexer_tile(const LAS unsigned char* buf, const f16x8 (&af)[2][8], const f32x4 (&wv)[2][4], float* sc0, float* sc1, int kt, int r32, int h2) {
;     ...
;     f16x8 bfr[2][8];
; #pragma unroll
;     for (int sub = 0; sub < 2; ++sub)
; #pragma unroll
;         for (int ks = 0; ks < 8; ++ks) bfr[sub][ks] = *(const LAS f16x8*)(buf + (32 * sub + r32) * KT_ROWB + (16 * ks + 8 * h2) * 2);
;     __builtin_amdgcn_sched_barrier(0);
; #pragma unroll
;     for (int sub = 0; sub < 2; ++sub) {
;         f32x16 c0, c1;
; #pragma unroll
;         for (int i = 0; i < 16; ++i) { c0[i] = 0.f; c1[i] = 0.f; }
; #pragma unroll
;         for (int ks = 0; ks < 8; ++ks) { c0 = __builtin_amdgcn_mfma_f32_32x32x16_f16(af[0][ks], bfr[sub][ks], c0, 0, 0, 0); c1 = __builtin_amdgcn_mfma_f32_32x32x16_f16(af[1][ks], bfr[sub][ks], c1, 0, 0, 0); }
;         f32x2_t a0 = {0.f, 0.f}, a1 = {0.f, 0.f};
; #pragma unroll
;         for (int q = 0; q < 4; ++q)
; #pragma unroll
;             for (int e = 0; e < 4; e += 2) {
;                 const f32x2_t r0 = {relu1(c0[4 * q + e]), relu1(c0[4 * q + e + 1])};
;                 const f32x2_t r1 = {relu1(c1[4 * q + e]), relu1(c1[4 * q + e + 1])};
;                 const f32x2_t w0 = {wv[0][q][e], wv[0][q][e + 1]}, w1 = {wv[1][q][e], wv[1][q][e + 1]};
;                 a0 = __builtin_elementwise_fma(r0, w0, a0); a1 = __builtin_elementwise_fma(r1, w1, a1); }
;         float s0 = a0.x + a0.y, s1 = a1.x + a1.y;
;         s0 += __shfl_xor(s0, 32); s1 += __shfl_xor(s1, 32);
;         if (h2 == 0) { sc0[kt * 64 + 32 * sub + r32] = s0; sc1[kt * 64 + 32 * sub + r32] = s1; }
;     }
; DI void indexer_phase(const unsigned short* QI, const unsigned short* KI16, const float* WI, float* SC, LAS unsigned char* lds, int tid, int bid, int G) {
;     ...
;                 indexer_tile(buf0, af, wv, sc0, sc1, kt, r32, h2);
;                 if (kt + 1 < nt) { *(LAS u32x4*)(buf1 + key0 * KT_ROWB + ch * 16) = b0; *(LAS u32x4*)(buf1 + (key0 + 32) * KT_ROWB + ch * 16) = b1; }
.Lp11_join2:
	v_mfma_f32_32x32x16_f16 v[0:15], v[82:85], v[250:253], 0
	v_mfma_f32_32x32x16_f16 v[0:15], v[86:89], v[210:213], v[0:15]
	v_mfma_f32_32x32x16_f16 v[0:15], v[90:93], v[214:217], v[0:15]
	s_nop 8
	v_max_i32_e32 v16, 0, v16
	v_max_i32_e32 v17, 0, v17
	v_fma_f32 v238, v16, v66, 0
	v_fma_f32 v239, v17, v67, 0
	v_max_i32_e32 v18, 0, v18
	v_max_i32_e32 v19, 0, v19
	v_fma_f32 v238, v18, v68, v238
	v_mfma_f32_32x32x16_f16 v[0:15], v[94:97], v[218:221], v[0:15]
	v_fma_f32 v239, v19, v69, v239
	v_max_i32_e32 v20, 0, v20
	v_max_i32_e32 v21, 0, v21
	v_fma_f32 v238, v20, v70, v238
	v_fma_f32 v239, v21, v71, v239
	v_max_i32_e32 v22, 0, v22
	v_max_i32_e32 v23, 0, v23
	v_mfma_f32_32x32x16_f16 v[0:15], v[98:101], v[222:225], v[0:15]
	v_fma_f32 v238, v22, v72, v238
	v_fma_f32 v239, v23, v73, v239
	v_max_i32_e32 v24, 0, v24
	v_max_i32_e32 v25, 0, v25
	v_fma_f32 v238, v24, v74, v238
	v_fma_f32 v239, v25, v75, v239
	v_mfma_f32_32x32x16_f16 v[0:15], v[102:105], v[226:229], v[0:15]
	v_max_i32_e32 v26, 0, v26
	v_max_i32_e32 v27, 0, v27
	v_fma_f32 v238, v26, v76, v238
	v_fma_f32 v239, v27, v77, v239
	v_max_i32_e32 v28, 0, v28
	v_max_i32_e32 v29, 0, v29
	v_mfma_f32_32x32x16_f16 v[0:15], v[106:109], v[230:233], v[0:15]
	v_fma_f32 v238, v28, v78, v238
	v_fma_f32 v239, v29, v79, v239
	v_max_i32_e32 v30, 0, v30
	v_max_i32_e32 v31, 0, v31
	v_fma_f32 v238, v30, v80, v238
	v_fma_f32 v239, v31, v81, v239
	v_mfma_f32_32x32x16_f16 v[0:15], v[110:113], v[234:237], v[0:15]
	v_add_f32_e32 v240, v238, v239
	v_mov_b32_e32 v241, v240
	v_lshlrev_b32_e32 v242, 2, v32
	s_nop 0
	v_permlane32_swap_b32_e32 v241, v240
	v_add_f32_e32 v241, v241, v240
	s_mov_b64 exec, s[4:5]
	global_store_dword v242, v241, s[24:25]
	s_mov_b64 exec, -1
	s_waitcnt lgkmcnt(0)
	v_mfma_f32_32x32x16_f16 v[16:31], v[34:37], v[174:177], 0
	v_mfma_f32_32x32x16_f16 v[16:31], v[38:41], v[170:173], v[16:31]
	v_mfma_f32_32x32x16_f16 v[16:31], v[42:45], v[166:169], v[16:31]
	s_nop 8
	v_max_i32_e32 v0, 0, v0
	v_max_i32_e32 v1, 0, v1
	v_fma_f32 v243, v0, v114, 0
	v_fma_f32 v244, v1, v115, 0
	v_max_i32_e32 v2, 0, v2
	v_max_i32_e32 v3, 0, v3
	v_fma_f32 v243, v2, v116, v243
	v_mfma_f32_32x32x16_f16 v[16:31], v[46:49], v[162:165], v[16:31]
	v_fma_f32 v244, v3, v117, v244
	v_max_i32_e32 v4, 0, v4
	v_max_i32_e32 v5, 0, v5
	v_fma_f32 v243, v4, v118, v243
	v_fma_f32 v244, v5, v119, v244
	v_max_i32_e32 v6, 0, v6
	v_max_i32_e32 v7, 0, v7
	v_mfma_f32_32x32x16_f16 v[16:31], v[50:53], v[158:161], v[16:31]
	v_fma_f32 v243, v6, v120, v243
	v_fma_f32 v244, v7, v121, v244
	v_max_i32_e32 v8, 0, v8
	v_max_i32_e32 v9, 0, v9
	v_fma_f32 v243, v8, v122, v243
	v_fma_f32 v244, v9, v123, v244
	v_mfma_f32_32x32x16_f16 v[16:31], v[54:57], v[154:157], v[16:31]
	v_max_i32_e32 v10, 0, v10
	v_max_i32_e32 v11, 0, v11
	v_fma_f32 v243, v10, v124, v243
	v_fma_f32 v244, v11, v125, v244
	v_max_i32_e32 v12, 0, v12
	v_max_i32_e32 v13, 0, v13
	v_mfma_f32_32x32x16_f16 v[16:31], v[58:61], v[150:153], v[16:31]
	v_fma_f32 v243, v12, v126, v243
	v_fma_f32 v244, v13, v127, v244
	v_max_i32_e32 v14, 0, v14
	v_max_i32_e32 v15, 0, v15
	v_fma_f32 v243, v14, v128, v243
	v_fma_f32 v244, v15, v129, v244
	v_mfma_f32_32x32x16_f16 v[16:31], v[62:65], v[146:149], v[16:31]
	v_add_f32_e32 v245, v243, v244
	v_mov_b32_e32 v246, v245
	v_lshlrev_b32_e32 v247, 2, v32
	s_nop 0
	v_permlane32_swap_b32_e32 v246, v245
	v_add_f32_e32 v246, v246, v245
	s_mov_b64 exec, s[4:5]
	global_store_dword v247, v246, s[26:27]
	s_mov_b64 exec, -1
	v_mfma_f32_32x32x16_f16 v[0:15], v[82:85], v[174:177], 0
	v_mfma_f32_32x32x16_f16 v[0:15], v[86:89], v[170:173], v[0:15]
	v_mfma_f32_32x32x16_f16 v[0:15], v[90:93], v[166:169], v[0:15]
	s_nop 8
	v_max_i32_e32 v16, 0, v16
	v_max_i32_e32 v17, 0, v17
	v_fma_f32 v238, v16, v66, 0
	v_fma_f32 v239, v17, v67, 0
	v_max_i32_e32 v18, 0, v18
	v_max_i32_e32 v19, 0, v19
	v_fma_f32 v238, v18, v68, v238
	v_mfma_f32_32x32x16_f16 v[0:15], v[94:97], v[162:165], v[0:15]
	v_fma_f32 v239, v19, v69, v239
	v_max_i32_e32 v20, 0, v20
	v_max_i32_e32 v21, 0, v21
	v_fma_f32 v238, v20, v70, v238
	v_fma_f32 v239, v21, v71, v239
	v_max_i32_e32 v22, 0, v22
	v_max_i32_e32 v23, 0, v23
	v_mfma_f32_32x32x16_f16 v[0:15], v[98:101], v[158:161], v[0:15]
	v_fma_f32 v238, v22, v72, v238
	v_fma_f32 v239, v23, v73, v239
	v_max_i32_e32 v24, 0, v24
	v_max_i32_e32 v25, 0, v25
	v_fma_f32 v238, v24, v74, v238
	v_fma_f32 v239, v25, v75, v239
	v_mfma_f32_32x32x16_f16 v[0:15], v[102:105], v[154:157], v[0:15]
	v_max_i32_e32 v26, 0, v26
	v_max_i32_e32 v27, 0, v27
	v_fma_f32 v238, v26, v76, v238
	v_fma_f32 v239, v27, v77, v239
	v_max_i32_e32 v28, 0, v28
	v_max_i32_e32 v29, 0, v29
	v_mfma_f32_32x32x16_f16 v[0:15], v[106:109], v[150:153], v[0:15]
	v_fma_f32 v238, v28, v78, v238
	v_fma_f32 v239, v29, v79, v239
	v_max_i32_e32 v30, 0, v30
	v_max_i32_e32 v31, 0, v31
	v_fma_f32 v238, v30, v80, v238
	v_fma_f32 v239, v31, v81, v239
	v_mfma_f32_32x32x16_f16 v[0:15], v[110:113], v[146:149], v[0:15]
	v_add_f32_e32 v240, v238, v239
	v_mov_b32_e32 v241, v240
	v_lshlrev_b32_e32 v242, 2, v32
	s_nop 0
	v_permlane32_swap_b32_e32 v241, v240
	v_add_f32_e32 v241, v241, v240
	s_mov_b64 exec, s[4:5]
	global_store_dword v242, v241, s[24:25] offset:128
	s_mov_b64 exec, -1
	s_mov_b32 s98, 1
	s_add_i32 s47, s11, -3
	s_cmp_lt_u32 s47, s42
	s_cselect_b64 s[30:31], -1, 0
	s_cmp_ge_u32 s47, s42
	s_cbranch_scc1 .LBB0_1853
	s_waitcnt vmcnt(8)
	ds_write_b128 v209, v[134:137] offset:17408
	ds_write_b128 v209, v[142:145] offset:26112

; #define LAS __attribute__((address_space(3)))
; DI void indexer_tile(const LAS unsigned char* buf, const f16x8 (&af)[2][8], const f32x4 (&wv)[2][4], float* sc0, float* sc1, int kt, int r32, int h2) {
;     ...
;     f16x8 bfr[2][8];
; #pragma unroll
;     for (int sub = 0; sub < 2; ++sub)
; #pragma unroll
;         for (int ks = 0; ks < 8; ++ks) bfr[sub][ks] = *(const LAS f16x8*)(buf + (32 * sub + r32) * KT_ROWB + (16 * ks + 8 * h2) * 2);
;     __builtin_amdgcn_sched_barrier(0);
; #pragma unroll
;     for (int sub = 0; sub < 2; ++sub) {
;         f32x16 c0, c1;
; #pragma unroll
;         for (int i = 0; i < 16; ++i) { c0[i] = 0.f; c1[i] = 0.f; }
; #pragma unroll
;         for (int ks = 0; ks < 8; ++ks) { c0 = __builtin_amdgcn_mfma_f32_32x32x16_f16(af[0][ks], bfr[sub][ks], c0, 0, 0, 0); c1 = __builtin_amdgcn_mfma_f32_32x32x16_f16(af[1][ks], bfr[sub][ks], c1, 0, 0, 0); }
;         f32x2_t a0 = {0.f, 0.f}, a1 = {0.f, 0.f};
; #pragma unroll
;         for (int q = 0; q < 4; ++q)
; #pragma unroll
;             for (int e = 0; e < 4; e += 2) {
;                 const f32x2_t r0 = {relu1(c0[4 * q + e]), relu1(c0[4 * q + e + 1])};
;                 const f32x2_t r1 = {relu1(c1[4 * q + e]), relu1(c1[4 * q + e + 1])};
;                 const f32x2_t w0 = {wv[0][q][e], wv[0][q][e + 1]}, w1 = {wv[1][q][e], wv[1][q][e + 1]};
;                 a0 = __builtin_elementwise_fma(r0, w0, a0); a1 = __builtin_elementwise_fma(r1, w1, a1); }
;         float s0 = a0.x + a0.y, s1 = a1.x + a1.y;
;         s0 += __shfl_xor(s0, 32); s1 += __shfl_xor(s1, 32);
;         if (h2 == 0) { sc0[kt * 64 + 32 * sub + r32] = s0; sc1[kt * 64 + 32 * sub + r32] = s1; }
;     }
; DI void indexer_phase(const unsigned short* QI, const unsigned short* KI16, const float* WI, float* SC, LAS unsigned char* lds, int tid, int bid, int G) {
;     ...
;                 if (kt + 3 < nt) { const unsigned short* p = src + (size_t)(kt + 3) * 64 * 128; b0 = *(const u32x4*)p; b1 = *(const u32x4*)(p + 32 * 128); }
;                 indexer_tile(buf1, af, wv, sc0, sc1, kt + 1, r32, h2);
.LBB0_1856:
	ds_read_b128 v[250:253], v207 offset:17408
	ds_read_b128 v[210:213], v207 offset:17440
	ds_read_b128 v[214:217], v207 offset:17472
	ds_read_b128 v[218:221], v207 offset:17504
	ds_read_b128 v[222:225], v207 offset:17536
	ds_read_b128 v[226:229], v207 offset:17568
	ds_read_b128 v[230:233], v207 offset:17600
	ds_read_b128 v[234:237], v207 offset:17632
	ds_read_b128 v[174:177], v207 offset:26112
	ds_read_b128 v[170:173], v207 offset:26144
	ds_read_b128 v[166:169], v207 offset:26176
	ds_read_b128 v[162:165], v207 offset:26208
	ds_read_b128 v[158:161], v207 offset:26240
	ds_read_b128 v[154:157], v207 offset:26272
	ds_read_b128 v[150:153], v207 offset:26304
	ds_read_b128 v[146:149], v207 offset:26336
	s_cmp_eq_u32 s98, 0
	s_cbranch_scc1 .Lp11_plain3
	s_waitcnt lgkmcnt(15)
	v_mfma_f32_32x32x16_f16 v[16:31], v[34:37], v[250:253], 0
	v_max_i32_e32 v0, 0, v0
	v_max_i32_e32 v1, 0, v1
	v_fma_f32 v243, v0, v114, 0
	v_fma_f32 v244, v1, v115, 0
	v_max_i32_e32 v2, 0, v2
	v_max_i32_e32 v3, 0, v3
	s_waitcnt lgkmcnt(14)
	v_mfma_f32_32x32x16_f16 v[16:31], v[38:41], v[210:213], v[16:31]
	v_fma_f32 v243, v2, v116, v243
	v_fma_f32 v244, v3, v117, v244
	v_max_i32_e32 v4, 0, v4
	v_max_i32_e32 v5, 0, v5
	v_fma_f32 v243, v4, v118, v243
	v_fma_f32 v244, v5, v119, v244
	s_waitcnt lgkmcnt(13)
	v_mfma_f32_32x32x16_f16 v[16:31], v[42:45], v[214:217], v[16:31]
	v_max_i32_e32 v6, 0, v6
	v_max_i32_e32 v7, 0, v7
	v_fma_f32 v243, v6, v120, v243
	v_fma_f32 v244, v7, v121, v244
	v_max_i32_e32 v8, 0, v8
	s_waitcnt lgkmcnt(12)
	v_mfma_f32_32x32x16_f16 v[16:31], v[46:49], v[218:221], v[16:31]
	v_max_i32_e32 v9, 0, v9
	v_fma_f32 v243, v8, v122, v243
	v_fma_f32 v244, v9, v123, v244
	v_max_i32_e32 v10, 0, v10
	v_max_i32_e32 v11, 0, v11
	s_waitcnt lgkmcnt(11)
	v_mfma_f32_32x32x16_f16 v[16:31], v[50:53], v[222:225], v[16:31]
	v_fma_f32 v243, v10, v124, v243
	v_fma_f32 v244, v11, v125, v244
	v_max_i32_e32 v12, 0, v12
	v_max_i32_e32 v13, 0, v13
	v_fma_f32 v243, v12, v126, v243
	s_waitcnt lgkmcnt(10)
	v_mfma_f32_32x32x16_f16 v[16:31], v[54:57], v[226:229], v[16:31]
	v_fma_f32 v244, v13, v127, v244
	v_max_i32_e32 v14, 0, v14
	v_max_i32_e32 v15, 0, v15
	v_fma_f32 v243, v14, v128, v243
	v_fma_f32 v244, v15, v129, v244
	s_waitcnt lgkmcnt(9)
	v_mfma_f32_32x32x16_f16 v[16:31], v[58:61], v[230:233], v[16:31]
	v_add_f32_e32 v245, v243, v244
	v_mov_b32_e32 v246, v245
	v_lshlrev_b32_e32 v247, 2, v32
	s_nop 0
	v_permlane32_swap_b32_e32 v246, v245
	s_waitcnt lgkmcnt(8)
	v_mfma_f32_32x32x16_f16 v[16:31], v[62:65], v[234:237], v[16:31]
	v_add_f32_e32 v246, v246, v245
	s_mov_b64 exec, s[4:5]
	global_store_dword v247, v246, s[26:27] offset:128
	s_mov_b64 exec, -1
	s_branch .Lp11_join3

; #define LAS __attribute__((address_space(3)))
; DI void indexer_tile(const LAS unsigned char* buf, const f16x8 (&af)[2][8], const f32x4 (&wv)[2][4], float* sc0, float* sc1, int kt, int r32, int h2) {
;     ...
;     f16x8 bfr[2][8];
; #pragma unroll
;     for (int sub = 0; sub < 2; ++sub)
; #pragma unroll
;         for (int ks = 0; ks < 8; ++ks) bfr[sub][ks] = *(const LAS f16x8*)(buf + (32 * sub + r32) * KT_ROWB + (16 * ks + 8 * h2) * 2);
;     __builtin_amdgcn_sched_barrier(0);
; #pragma unroll
;     for (int sub = 0; sub < 2; ++sub) {
;         f32x16 c0, c1;
; #pragma unroll
;         for (int i = 0; i < 16; ++i) { c0[i] = 0.f; c1[i] = 0.f; }
; #pragma unroll
;         for (int ks = 0; ks < 8; ++ks) { c0 = __builtin_amdgcn_mfma_f32_32x32x16_f16(af[0][ks], bfr[sub][ks], c0, 0, 0, 0); c1 = __builtin_amdgcn_mfma_f32_32x32x16_f16(af[1][ks], bfr[sub][ks], c1, 0, 0, 0); }
;         f32x2_t a0 = {0.f, 0.f}, a1 = {0.f, 0.f};
; #pragma unroll
;         for (int q = 0; q < 4; ++q)
; #pragma unroll
;             for (int e = 0; e < 4; e += 2) {
;                 const f32x2_t r0 = {relu1(c0[4 * q + e]), relu1(c0[4 * q + e + 1])};
;                 const f32x2_t r1 = {relu1(c1[4 * q + e]), relu1(c1[4 * q + e + 1])};
;                 const f32x2_t w0 = {wv[0][q][e], wv[0][q][e + 1]}, w1 = {wv[1][q][e], wv[1][q][e + 1]};
;                 a0 = __builtin_elementwise_fma(r0, w0, a0); a1 = __builtin_elementwise_fma(r1, w1, a1); }
;         float s0 = a0.x + a0.y, s1 = a1.x + a1.y;
;         s0 += __shfl_xor(s0, 32); s1 += __shfl_xor(s1, 32);
;         if (h2 == 0) { sc0[kt * 64 + 32 * sub + r32] = s0; sc1[kt * 64 + 32 * sub + r32] = s1; }
;     }
; DI void indexer_phase(const unsigned short* QI, const unsigned short* KI16, const float* WI, float* SC, LAS unsigned char* lds, int tid, int bid, int G) {
;     ...
;                 if (kt + 2 < nt) { *(LAS u32x4*)(buf0 + key0 * KT_ROWB + ch * 16) = a0; *(LAS u32x4*)(buf0 + (key0 + 32) * KT_ROWB + ch * 16) = a1; }
;                 __syncthreads();
.Lp11_join3:
	v_mfma_f32_32x32x16_f16 v[0:15], v[82:85], v[250:253], 0
	v_mfma_f32_32x32x16_f16 v[0:15], v[86:89], v[210:213], v[0:15]
	v_mfma_f32_32x32x16_f16 v[0:15], v[90:93], v[214:217], v[0:15]
	s_nop 8
	v_max_i32_e32 v16, 0, v16
	v_max_i32_e32 v17, 0, v17
	v_fma_f32 v238, v16, v66, 0
	v_fma_f32 v239, v17, v67, 0
	v_max_i32_e32 v18, 0, v18
	v_max_i32_e32 v19, 0, v19
	v_fma_f32 v238, v18, v68, v238
	v_mfma_f32_32x32x16_f16 v[0:15], v[94:97], v[218:221], v[0:15]
	v_fma_f32 v239, v19, v69, v239
	v_max_i32_e32 v20, 0, v20
	v_max_i32_e32 v21, 0, v21
	v_fma_f32 v238, v20, v70, v238
	v_fma_f32 v239, v21, v71, v239
	v_max_i32_e32 v22, 0, v22
	v_max_i32_e32 v23, 0, v23
	v_mfma_f32_32x32x16_f16 v[0:15], v[98:101], v[222:225], v[0:15]
	v_fma_f32 v238, v22, v72, v238
	v_fma_f32 v239, v23, v73, v239
	v_max_i32_e32 v24, 0, v24
	v_max_i32_e32 v25, 0, v25
	v_fma_f32 v238, v24, v74, v238
	v_fma_f32 v239, v25, v75, v239
	v_mfma_f32_32x32x16_f16 v[0:15], v[102:105], v[226:229], v[0:15]
	v_max_i32_e32 v26, 0, v26
	v_max_i32_e32 v27, 0, v27
	v_fma_f32 v238, v26, v76, v238
	v_fma_f32 v239, v27, v77, v239
	v_max_i32_e32 v28, 0, v28
	v_max_i32_e32 v29, 0, v29
	v_mfma_f32_32x32x16_f16 v[0:15], v[106:109], v[230:233], v[0:15]
	v_fma_f32 v238, v28, v78, v238
	v_fma_f32 v239, v29, v79, v239
	v_max_i32_e32 v30, 0, v30
	v_max_i32_e32 v31, 0, v31
	v_fma_f32 v238, v30, v80, v238
	v_fma_f32 v239, v31, v81, v239
	v_mfma_f32_32x32x16_f16 v[0:15], v[110:113], v[234:237], v[0:15]
	v_add_f32_e32 v240, v238, v239
	v_mov_b32_e32 v241, v240
	v_lshlrev_b32_e32 v242, 2, v32
	s_nop 0
	v_permlane32_swap_b32_e32 v241, v240
	v_add_f32_e32 v241, v241, v240
	s_mov_b64 exec, s[4:5]
	global_store_dword v242, v241, s[24:25] offset:256
	s_mov_b64 exec, -1
	s_waitcnt lgkmcnt(0)
	v_mfma_f32_32x32x16_f16 v[16:31], v[34:37], v[174:177], 0
	v_mfma_f32_32x32x16_f16 v[16:31], v[38:41], v[170:173], v[16:31]
	v_mfma_f32_32x32x16_f16 v[16:31], v[42:45], v[166:169], v[16:31]
	s_nop 8
	v_max_i32_e32 v0, 0, v0
	v_max_i32_e32 v1, 0, v1
	v_fma_f32 v243, v0, v114, 0
	v_fma_f32 v244, v1, v115, 0
	v_max_i32_e32 v2, 0, v2
	v_max_i32_e32 v3, 0, v3
	v_fma_f32 v243, v2, v116, v243
	v_mfma_f32_32x32x16_f16 v[16:31], v[46:49], v[162:165], v[16:31]
	v_fma_f32 v244, v3, v117, v244
	v_max_i32_e32 v4, 0, v4
	v_max_i32_e32 v5, 0, v5
	v_fma_f32 v243, v4, v118, v243
	v_fma_f32 v244, v5, v119, v244
	v_max_i32_e32 v6, 0, v6
	v_max_i32_e32 v7, 0, v7
	v_mfma_f32_32x32x16_f16 v[16:31], v[50:53], v[158:161], v[16:31]
	v_fma_f32 v243, v6, v120, v243
	v_fma_f32 v244, v7, v121, v244
	v_max_i32_e32 v8, 0, v8
	v_max_i32_e32 v9, 0, v9
	v_fma_f32 v243, v8, v122, v243
	v_fma_f32 v244, v9, v123, v244
	v_mfma_f32_32x32x16_f16 v[16:31], v[54:57], v[154:157], v[16:31]
	v_max_i32_e32 v10, 0, v10
	v_max_i32_e32 v11, 0, v11
	v_fma_f32 v243, v10, v124, v243
	v_fma_f32 v244, v11, v125, v244
	v_max_i32_e32 v12, 0, v12
	v_max_i32_e32 v13, 0, v13
	v_mfma_f32_32x32x16_f16 v[16:31], v[58:61], v[150:153], v[16:31]
	v_fma_f32 v243, v12, v126, v243
	v_fma_f32 v244, v13, v127, v244
	v_max_i32_e32 v14, 0, v14
	v_max_i32_e32 v15, 0, v15
	v_fma_f32 v243, v14, v128, v243
	v_fma_f32 v244, v15, v129, v244
	v_mfma_f32_32x32x16_f16 v[16:31], v[62:65], v[146:149], v[16:31]
	v_add_f32_e32 v245, v243, v244
	v_mov_b32_e32 v246, v245
	v_lshlrev_b32_e32 v247, 2, v32
	s_nop 0
	v_permlane32_swap_b32_e32 v246, v245
	v_add_f32_e32 v246, v246, v245
	s_mov_b64 exec, s[4:5]
	global_store_dword v247, v246, s[26:27] offset:256
	s_mov_b64 exec, -1
	v_mfma_f32_32x32x16_f16 v[0:15], v[82:85], v[174:177], 0
	v_mfma_f32_32x32x16_f16 v[0:15], v[86:89], v[170:173], v[0:15]
	v_mfma_f32_32x32x16_f16 v[0:15], v[90:93], v[166:169], v[0:15]
	s_nop 8
	v_max_i32_e32 v16, 0, v16
	v_max_i32_e32 v17, 0, v17
	v_fma_f32 v238, v16, v66, 0
	v_fma_f32 v239, v17, v67, 0
	v_max_i32_e32 v18, 0, v18
	v_max_i32_e32 v19, 0, v19
	v_fma_f32 v238, v18, v68, v238
	v_mfma_f32_32x32x16_f16 v[0:15], v[94:97], v[162:165], v[0:15]
	v_fma_f32 v239, v19, v69, v239
	v_max_i32_e32 v20, 0, v20
	v_max_i32_e32 v21, 0, v21
	v_fma_f32 v238, v20, v70, v238
	v_fma_f32 v239, v21, v71, v239
	v_max_i32_e32 v22, 0, v22
	v_max_i32_e32 v23, 0, v23
	v_mfma_f32_32x32x16_f16 v[0:15], v[98:101], v[158:161], v[0:15]
	v_fma_f32 v238, v22, v72, v238
	v_fma_f32 v239, v23, v73, v239
	v_max_i32_e32 v24, 0, v24
	v_max_i32_e32 v25, 0, v25
	v_fma_f32 v238, v24, v74, v238
	v_fma_f32 v239, v25, v75, v239
	v_mfma_f32_32x32x16_f16 v[0:15], v[102:105], v[154:157], v[0:15]
	v_max_i32_e32 v26, 0, v26
	v_max_i32_e32 v27, 0, v27
	v_fma_f32 v238, v26, v76, v238
	v_fma_f32 v239, v27, v77, v239
	v_max_i32_e32 v28, 0, v28
	v_max_i32_e32 v29, 0, v29
	v_mfma_f32_32x32x16_f16 v[0:15], v[106:109], v[150:153], v[0:15]
	v_fma_f32 v238, v28, v78, v238
	v_fma_f32 v239, v29, v79, v239
	v_max_i32_e32 v30, 0, v30
	v_max_i32_e32 v31, 0, v31
	v_fma_f32 v238, v30, v80, v238
	v_fma_f32 v239, v31, v81, v239
	v_mfma_f32_32x32x16_f16 v[0:15], v[110:113], v[146:149], v[0:15]
	v_add_f32_e32 v240, v238, v239
	v_mov_b32_e32 v241, v240
	v_lshlrev_b32_e32 v242, 2, v32
	s_nop 0
	v_permlane32_swap_b32_e32 v241, v240
	v_add_f32_e32 v241, v241, v240
	s_mov_b64 exec, s[4:5]
	global_store_dword v242, v241, s[24:25] offset:384
	s_mov_b64 exec, -1
	s_mov_b32 s98, 1
	s_andn2_b64 vcc, exec, s[28:29]
	s_cbranch_vccnz .LBB0_1844
	s_waitcnt vmcnt(7)
	ds_write_b128 v209, v[130:133]
	ds_write_b128 v209, v[138:141] offset:8704
	s_branch .LBB0_1844

; #define LAS __attribute__((address_space(3)))
; DI void indexer_tile(const LAS unsigned char* buf, const f16x8 (&af)[2][8], const f32x4 (&wv)[2][4], float* sc0, float* sc1, int kt, int r32, int h2) {
;     ...
;     f16x8 bfr[2][8];
; #pragma unroll
;     for (int sub = 0; sub < 2; ++sub)
; #pragma unroll
;         for (int ks = 0; ks < 8; ++ks) bfr[sub][ks] = *(const LAS f16x8*)(buf + (32 * sub + r32) * KT_ROWB + (16 * ks + 8 * h2) * 2);
;     __builtin_amdgcn_sched_barrier(0);
; #pragma unroll
;     for (int sub = 0; sub < 2; ++sub) {
;         f32x16 c0, c1;
; #pragma unroll
;         for (int i = 0; i < 16; ++i) { c0[i] = 0.f; c1[i] = 0.f; }
; #pragma unroll
;         for (int ks = 0; ks < 8; ++ks) { c0 = __builtin_amdgcn_mfma_f32_32x32x16_f16(af[0][ks], bfr[sub][ks], c0, 0, 0, 0); c1 = __builtin_amdgcn_mfma_f32_32x32x16_f16(af[1][ks], bfr[sub][ks], c1, 0, 0, 0); }
;         f32x2_t a0 = {0.f, 0.f}, a1 = {0.f, 0.f};
; #pragma unroll
;         for (int q = 0; q < 4; ++q)
; #pragma unroll
;             for (int e = 0; e < 4; e += 2) {
;                 const f32x2_t r0 = {relu1(c0[4 * q + e]), relu1(c0[4 * q + e + 1])};
;                 const f32x2_t r1 = {relu1(c1[4 * q + e]), relu1(c1[4 * q + e + 1])};
;                 const f32x2_t w0 = {wv[0][q][e], wv[0][q][e + 1]}, w1 = {wv[1][q][e], wv[1][q][e + 1]};
;                 a0 = __builtin_elementwise_fma(r0, w0, a0); a1 = __builtin_elementwise_fma(r1, w1, a1); }
;         float s0 = a0.x + a0.y, s1 = a1.x + a1.y;
;         s0 += __shfl_xor(s0, 32); s1 += __shfl_xor(s1, 32);
;         if (h2 == 0) { sc0[kt * 64 + 32 * sub + r32] = s0; sc1[kt * 64 + 32 * sub + r32] = s1; }
;     }
; DI void indexer_phase(const unsigned short* QI, const unsigned short* KI16, const float* WI, float* SC, LAS unsigned char* lds, int tid, int bid, int G) {
;     ...
;             for (int kt = 0; kt < nt; kt += 2) {
;                 if (kt + 2 < nt) { const unsigned short* p = src + (size_t)(kt + 2) * 64 * 128; a0 = *(const u32x4*)p; a1 = *(const u32x4*)(p + 32 * 128); }
;                 indexer_tile(buf0, af, wv, sc0, sc1, kt, r32, h2);
.LBB0_1871:
	ds_read_b128 v[250:253], v207
	ds_read_b128 v[210:213], v207 offset:32
	ds_read_b128 v[214:217], v207 offset:64
	ds_read_b128 v[218:221], v207 offset:96
	ds_read_b128 v[222:225], v207 offset:128
	ds_read_b128 v[226:229], v207 offset:160
	ds_read_b128 v[230:233], v207 offset:192
	ds_read_b128 v[234:237], v207 offset:224
	ds_read_b128 v[176:179], v207 offset:8704
	ds_read_b128 v[172:175], v207 offset:8736
	ds_read_b128 v[168:171], v207 offset:8768
	ds_read_b128 v[164:167], v207 offset:8800
	ds_read_b128 v[160:163], v207 offset:8832
	ds_read_b128 v[156:159], v207 offset:8864
	ds_read_b128 v[152:155], v207 offset:8896
	ds_read_b128 v[148:151], v207 offset:8928
	s_cmp_eq_u32 s98, 0
	s_cbranch_scc1 .Lp11_plain4
	s_waitcnt lgkmcnt(15)
	v_mfma_f32_32x32x16_f16 v[16:31], v[36:39], v[250:253], 0
	v_max_i32_e32 v0, 0, v0
	v_max_i32_e32 v1, 0, v1
	v_fma_f32 v243, v0, v116, 0
	v_fma_f32 v244, v1, v117, 0
	v_max_i32_e32 v2, 0, v2
	v_max_i32_e32 v3, 0, v3
	s_waitcnt lgkmcnt(14)
	v_mfma_f32_32x32x16_f16 v[16:31], v[40:43], v[210:213], v[16:31]
	v_fma_f32 v243, v2, v118, v243
	v_fma_f32 v244, v3, v119, v244
	v_max_i32_e32 v4, 0, v4
	v_max_i32_e32 v5, 0, v5
	v_fma_f32 v243, v4, v120, v243
	v_fma_f32 v244, v5, v121, v244
	s_waitcnt lgkmcnt(13)
	v_mfma_f32_32x32x16_f16 v[16:31], v[44:47], v[214:217], v[16:31]
	v_max_i32_e32 v6, 0, v6
	v_max_i32_e32 v7, 0, v7
	v_fma_f32 v243, v6, v122, v243
	v_fma_f32 v244, v7, v123, v244
	v_max_i32_e32 v8, 0, v8
	s_waitcnt lgkmcnt(12)
	v_mfma_f32_32x32x16_f16 v[16:31], v[48:51], v[218:221], v[16:31]
	v_max_i32_e32 v9, 0, v9
	v_fma_f32 v243, v8, v124, v243
	v_fma_f32 v244, v9, v125, v244
	v_max_i32_e32 v10, 0, v10
	v_max_i32_e32 v11, 0, v11
	s_waitcnt lgkmcnt(11)
	v_mfma_f32_32x32x16_f16 v[16:31], v[52:55], v[222:225], v[16:31]
	v_fma_f32 v243, v10, v126, v243
	v_fma_f32 v244, v11, v127, v244
	v_max_i32_e32 v12, 0, v12
	v_max_i32_e32 v13, 0, v13
	v_fma_f32 v243, v12, v128, v243
	s_waitcnt lgkmcnt(10)
	v_mfma_f32_32x32x16_f16 v[16:31], v[56:59], v[226:229], v[16:31]
	v_fma_f32 v244, v13, v129, v244
	v_max_i32_e32 v14, 0, v14
	v_max_i32_e32 v15, 0, v15
	v_fma_f32 v243, v14, v130, v243
	v_fma_f32 v244, v15, v131, v244
	s_waitcnt lgkmcnt(9)
	v_mfma_f32_32x32x16_f16 v[16:31], v[60:63], v[230:233], v[16:31]
	v_add_f32_e32 v245, v243, v244
	v_mov_b32_e32 v246, v245
	v_lshlrev_b32_e32 v247, 2, v32
	s_nop 0
	v_permlane32_swap_b32_e32 v246, v245
	s_waitcnt lgkmcnt(8)
	v_mfma_f32_32x32x16_f16 v[16:31], v[64:67], v[234:237], v[16:31]
	v_add_f32_e32 v246, v246, v245
	s_mov_b64 exec, s[4:5]
	global_store_dword v247, v246, s[8:9] offset:-128
	s_mov_b64 exec, -1
	s_branch .Lp11_join4

; #define LAS __attribute__((address_space(3)))
; DI void indexer_tile(const LAS unsigned char* buf, const f16x8 (&af)[2][8], const f32x4 (&wv)[2][4], float* sc0, float* sc1, int kt, int r32, int h2) {
;     ...
;     f16x8 bfr[2][8];
; #pragma unroll
;     for (int sub = 0; sub < 2; ++sub)
; #pragma unroll
;         for (int ks = 0; ks < 8; ++ks) bfr[sub][ks] = *(const LAS f16x8*)(buf + (32 * sub + r32) * KT_ROWB + (16 * ks + 8 * h2) * 2);
;     __builtin_amdgcn_sched_barrier(0);
; #pragma unroll
;     for (int sub = 0; sub < 2; ++sub) {
;         f32x16 c0, c1;
; #pragma unroll
;         for (int i = 0; i < 16; ++i) { c0[i] = 0.f; c1[i] = 0.f; }
; #pragma unroll
;         for (int ks = 0; ks < 8; ++ks) { c0 = __builtin_amdgcn_mfma_f32_32x32x16_f16(af[0][ks], bfr[sub][ks], c0, 0, 0, 0); c1 = __builtin_amdgcn_mfma_f32_32x32x16_f16(af[1][ks], bfr[sub][ks], c1, 0, 0, 0); }
;         f32x2_t a0 = {0.f, 0.f}, a1 = {0.f, 0.f};
; #pragma unroll
;         for (int q = 0; q < 4; ++q)
; #pragma unroll
;             for (int e = 0; e < 4; e += 2) {
;                 const f32x2_t r0 = {relu1(c0[4 * q + e]), relu1(c0[4 * q + e + 1])};
;                 const f32x2_t r1 = {relu1(c1[4 * q + e]), relu1(c1[4 * q + e + 1])};
;                 const f32x2_t w0 = {wv[0][q][e], wv[0][q][e + 1]}, w1 = {wv[1][q][e], wv[1][q][e + 1]};
;                 a0 = __builtin_elementwise_fma(r0, w0, a0); a1 = __builtin_elementwise_fma(r1, w1, a1); }
;         float s0 = a0.x + a0.y, s1 = a1.x + a1.y;
;         s0 += __shfl_xor(s0, 32); s1 += __shfl_xor(s1, 32);
;         if (h2 == 0) { sc0[kt * 64 + 32 * sub + r32] = s0; sc1[kt * 64 + 32 * sub + r32] = s1; }
;     }
; DI void indexer_phase(const unsigned short* QI, const unsigned short* KI16, const float* WI, float* SC, LAS unsigned char* lds, int tid, int bid, int G) {
;     ...
;                 indexer_tile(buf0, af, wv, sc0, sc1, kt, r32, h2);
;                 if (kt + 1 < nt) { *(LAS u32x4*)(buf1 + key0 * KT_ROWB + ch * 16) = b0; *(LAS u32x4*)(buf1 + (key0 + 32) * KT_ROWB + ch * 16) = b1; }
.Lp11_join4:
	v_mfma_f32_32x32x16_f16 v[0:15], v[84:87], v[250:253], 0
	v_mfma_f32_32x32x16_f16 v[0:15], v[88:91], v[210:213], v[0:15]
	v_mfma_f32_32x32x16_f16 v[0:15], v[92:95], v[214:217], v[0:15]
	s_nop 8
	v_max_i32_e32 v16, 0, v16
	v_max_i32_e32 v17, 0, v17
	v_fma_f32 v238, v16, v68, 0
	v_fma_f32 v239, v17, v69, 0
	v_max_i32_e32 v18, 0, v18
	v_max_i32_e32 v19, 0, v19
	v_fma_f32 v238, v18, v70, v238
	v_mfma_f32_32x32x16_f16 v[0:15], v[96:99], v[218:221], v[0:15]
	v_fma_f32 v239, v19, v71, v239
	v_max_i32_e32 v20, 0, v20
	v_max_i32_e32 v21, 0, v21
	v_fma_f32 v238, v20, v72, v238
	v_fma_f32 v239, v21, v73, v239
	v_max_i32_e32 v22, 0, v22
	v_max_i32_e32 v23, 0, v23
	v_mfma_f32_32x32x16_f16 v[0:15], v[100:103], v[222:225], v[0:15]
	v_fma_f32 v238, v22, v74, v238
	v_fma_f32 v239, v23, v75, v239
	v_max_i32_e32 v24, 0, v24
	v_max_i32_e32 v25, 0, v25
	v_fma_f32 v238, v24, v76, v238
	v_fma_f32 v239, v25, v77, v239
	v_mfma_f32_32x32x16_f16 v[0:15], v[104:107], v[226:229], v[0:15]
	v_max_i32_e32 v26, 0, v26
	v_max_i32_e32 v27, 0, v27
	v_fma_f32 v238, v26, v78, v238
	v_fma_f32 v239, v27, v79, v239
	v_max_i32_e32 v28, 0, v28
	v_max_i32_e32 v29, 0, v29
	v_mfma_f32_32x32x16_f16 v[0:15], v[108:111], v[230:233], v[0:15]
	v_fma_f32 v238, v28, v80, v238
	v_fma_f32 v239, v29, v81, v239
	v_max_i32_e32 v30, 0, v30
	v_max_i32_e32 v31, 0, v31
	v_fma_f32 v238, v30, v82, v238
	v_fma_f32 v239, v31, v83, v239
	v_mfma_f32_32x32x16_f16 v[0:15], v[112:115], v[234:237], v[0:15]
	v_add_f32_e32 v240, v238, v239
	v_mov_b32_e32 v241, v240
	v_lshlrev_b32_e32 v242, 2, v32
	s_nop 0
	v_permlane32_swap_b32_e32 v241, v240
	v_add_f32_e32 v241, v241, v240
	s_mov_b64 exec, s[4:5]
	global_store_dword v242, v241, s[6:7]
	s_mov_b64 exec, -1
	s_waitcnt lgkmcnt(0)
	v_mfma_f32_32x32x16_f16 v[16:31], v[36:39], v[176:179], 0
	v_mfma_f32_32x32x16_f16 v[16:31], v[40:43], v[172:175], v[16:31]
	v_mfma_f32_32x32x16_f16 v[16:31], v[44:47], v[168:171], v[16:31]
	s_nop 8
	v_max_i32_e32 v0, 0, v0
	v_max_i32_e32 v1, 0, v1
	v_fma_f32 v243, v0, v116, 0
	v_fma_f32 v244, v1, v117, 0
	v_max_i32_e32 v2, 0, v2
	v_max_i32_e32 v3, 0, v3
	v_fma_f32 v243, v2, v118, v243
	v_mfma_f32_32x32x16_f16 v[16:31], v[48:51], v[164:167], v[16:31]
	v_fma_f32 v244, v3, v119, v244
	v_max_i32_e32 v4, 0, v4
	v_max_i32_e32 v5, 0, v5
	v_fma_f32 v243, v4, v120, v243
	v_fma_f32 v244, v5, v121, v244
	v_max_i32_e32 v6, 0, v6
	v_max_i32_e32 v7, 0, v7
	v_mfma_f32_32x32x16_f16 v[16:31], v[52:55], v[160:163], v[16:31]
	v_fma_f32 v243, v6, v122, v243
	v_fma_f32 v244, v7, v123, v244
	v_max_i32_e32 v8, 0, v8
	v_max_i32_e32 v9, 0, v9
	v_fma_f32 v243, v8, v124, v243
	v_fma_f32 v244, v9, v125, v244
	v_mfma_f32_32x32x16_f16 v[16:31], v[56:59], v[156:159], v[16:31]
	v_max_i32_e32 v10, 0, v10
	v_max_i32_e32 v11, 0, v11
	v_fma_f32 v243, v10, v126, v243
	v_fma_f32 v244, v11, v127, v244
	v_max_i32_e32 v12, 0, v12
	v_max_i32_e32 v13, 0, v13
	v_mfma_f32_32x32x16_f16 v[16:31], v[60:63], v[152:155], v[16:31]
	v_fma_f32 v243, v12, v128, v243
	v_fma_f32 v244, v13, v129, v244
	v_max_i32_e32 v14, 0, v14
	v_max_i32_e32 v15, 0, v15
	v_fma_f32 v243, v14, v130, v243
	v_fma_f32 v244, v15, v131, v244
	v_mfma_f32_32x32x16_f16 v[16:31], v[64:67], v[148:151], v[16:31]
	v_add_f32_e32 v245, v243, v244
	v_mov_b32_e32 v246, v245
	v_lshlrev_b32_e32 v247, 2, v32
	s_nop 0
	v_permlane32_swap_b32_e32 v246, v245
	v_add_f32_e32 v246, v246, v245
	s_mov_b64 exec, s[4:5]
	global_store_dword v247, v246, s[8:9]
	s_mov_b64 exec, -1
	v_mfma_f32_32x32x16_f16 v[0:15], v[84:87], v[176:179], 0
	v_mfma_f32_32x32x16_f16 v[0:15], v[88:91], v[172:175], v[0:15]
	v_mfma_f32_32x32x16_f16 v[0:15], v[92:95], v[168:171], v[0:15]
	s_nop 8
	v_max_i32_e32 v16, 0, v16
	v_max_i32_e32 v17, 0, v17
	v_fma_f32 v238, v16, v68, 0
	v_fma_f32 v239, v17, v69, 0
	v_max_i32_e32 v18, 0, v18
	v_max_i32_e32 v19, 0, v19
	v_fma_f32 v238, v18, v70, v238
	v_mfma_f32_32x32x16_f16 v[0:15], v[96:99], v[164:167], v[0:15]
	v_fma_f32 v239, v19, v71, v239
	v_max_i32_e32 v20, 0, v20
	v_max_i32_e32 v21, 0, v21
	v_fma_f32 v238, v20, v72, v238
	v_fma_f32 v239, v21, v73, v239
	v_max_i32_e32 v22, 0, v22
	v_max_i32_e32 v23, 0, v23
	v_mfma_f32_32x32x16_f16 v[0:15], v[100:103], v[160:163], v[0:15]
	v_fma_f32 v238, v22, v74, v238
	v_fma_f32 v239, v23, v75, v239
	v_max_i32_e32 v24, 0, v24
	v_max_i32_e32 v25, 0, v25
	v_fma_f32 v238, v24, v76, v238
	v_fma_f32 v239, v25, v77, v239
	v_mfma_f32_32x32x16_f16 v[0:15], v[104:107], v[156:159], v[0:15]
	v_max_i32_e32 v26, 0, v26
	v_max_i32_e32 v27, 0, v27
	v_fma_f32 v238, v26, v78, v238
	v_fma_f32 v239, v27, v79, v239
	v_max_i32_e32 v28, 0, v28
	v_max_i32_e32 v29, 0, v29
	v_mfma_f32_32x32x16_f16 v[0:15], v[108:111], v[152:155], v[0:15]
	v_fma_f32 v238, v28, v80, v238
	v_fma_f32 v239, v29, v81, v239
	v_max_i32_e32 v30, 0, v30
	v_max_i32_e32 v31, 0, v31
	v_fma_f32 v238, v30, v82, v238
	v_fma_f32 v239, v31, v83, v239
	v_mfma_f32_32x32x16_f16 v[0:15], v[112:115], v[148:151], v[0:15]
	v_add_f32_e32 v240, v238, v239
	v_mov_b32_e32 v241, v240
	v_lshlrev_b32_e32 v242, 2, v32
	s_nop 0
	v_permlane32_swap_b32_e32 v241, v240
	v_add_f32_e32 v241, v241, v240
	s_mov_b64 exec, s[4:5]
	global_store_dword v242, v241, s[6:7] offset:128
	s_mov_b64 exec, -1
	s_mov_b32 s98, 1
	s_add_i32 s24, s14, -3
	s_cmp_lt_i32 s24, s41
	s_cselect_b64 s[12:13], -1, 0
	s_cmp_ge_i32 s24, s41
	s_cbranch_scc1 .LBB0_1877
	s_waitcnt vmcnt(8)
	ds_write_b128 v209, v[140:143] offset:17408
	ds_write_b128 v209, v[144:147] offset:26112

; #define LAS __attribute__((address_space(3)))
; DI void indexer_tile(const LAS unsigned char* buf, const f16x8 (&af)[2][8], const f32x4 (&wv)[2][4], float* sc0, float* sc1, int kt, int r32, int h2) {
;     ...
;     f16x8 bfr[2][8];
; #pragma unroll
;     for (int sub = 0; sub < 2; ++sub)
; #pragma unroll
;         for (int ks = 0; ks < 8; ++ks) bfr[sub][ks] = *(const LAS f16x8*)(buf + (32 * sub + r32) * KT_ROWB + (16 * ks + 8 * h2) * 2);
;     __builtin_amdgcn_sched_barrier(0);
; #pragma unroll
;     for (int sub = 0; sub < 2; ++sub) {
;         f32x16 c0, c1;
; #pragma unroll
;         for (int i = 0; i < 16; ++i) { c0[i] = 0.f; c1[i] = 0.f; }
; #pragma unroll
;         for (int ks = 0; ks < 8; ++ks) { c0 = __builtin_amdgcn_mfma_f32_32x32x16_f16(af[0][ks], bfr[sub][ks], c0, 0, 0, 0); c1 = __builtin_amdgcn_mfma_f32_32x32x16_f16(af[1][ks], bfr[sub][ks], c1, 0, 0, 0); }
;         f32x2_t a0 = {0.f, 0.f}, a1 = {0.f, 0.f};
; #pragma unroll
;         for (int q = 0; q < 4; ++q)
; #pragma unroll
;             for (int e = 0; e < 4; e += 2) {
;                 const f32x2_t r0 = {relu1(c0[4 * q + e]), relu1(c0[4 * q + e + 1])};
;                 const f32x2_t r1 = {relu1(c1[4 * q + e]), relu1(c1[4 * q + e + 1])};
;                 const f32x2_t w0 = {wv[0][q][e], wv[0][q][e + 1]}, w1 = {wv[1][q][e], wv[1][q][e + 1]};
;                 a0 = __builtin_elementwise_fma(r0, w0, a0); a1 = __builtin_elementwise_fma(r1, w1, a1); }
;         float s0 = a0.x + a0.y, s1 = a1.x + a1.y;
;         s0 += __shfl_xor(s0, 32); s1 += __shfl_xor(s1, 32);
;         if (h2 == 0) { sc0[kt * 64 + 32 * sub + r32] = s0; sc1[kt * 64 + 32 * sub + r32] = s1; }
;     }
; DI void indexer_phase(const unsigned short* QI, const unsigned short* KI16, const float* WI, float* SC, LAS unsigned char* lds, int tid, int bid, int G) {
;     ...
;                 if (kt + 3 < nt) { const unsigned short* p = src + (size_t)(kt + 3) * 64 * 128; b0 = *(const u32x4*)p; b1 = *(const u32x4*)(p + 32 * 128); }
;                 indexer_tile(buf1, af, wv, sc0, sc1, kt + 1, r32, h2);
.LBB0_1880:
	ds_read_b128 v[250:253], v207 offset:17408
	ds_read_b128 v[210:213], v207 offset:17440
	ds_read_b128 v[214:217], v207 offset:17472
	ds_read_b128 v[218:221], v207 offset:17504
	ds_read_b128 v[222:225], v207 offset:17536
	ds_read_b128 v[226:229], v207 offset:17568
	ds_read_b128 v[230:233], v207 offset:17600
	ds_read_b128 v[234:237], v207 offset:17632
	ds_read_b128 v[176:179], v207 offset:26112
	ds_read_b128 v[172:175], v207 offset:26144
	ds_read_b128 v[168:171], v207 offset:26176
	ds_read_b128 v[164:167], v207 offset:26208
	ds_read_b128 v[160:163], v207 offset:26240
	ds_read_b128 v[156:159], v207 offset:26272
	ds_read_b128 v[152:155], v207 offset:26304
	ds_read_b128 v[148:151], v207 offset:26336
	s_cmp_eq_u32 s98, 0
	s_cbranch_scc1 .Lp11_plain5
	s_waitcnt lgkmcnt(15)
	v_mfma_f32_32x32x16_f16 v[16:31], v[36:39], v[250:253], 0
	v_max_i32_e32 v0, 0, v0
	v_max_i32_e32 v1, 0, v1
	v_fma_f32 v243, v0, v116, 0
	v_fma_f32 v244, v1, v117, 0
	v_max_i32_e32 v2, 0, v2
	v_max_i32_e32 v3, 0, v3
	s_waitcnt lgkmcnt(14)
	v_mfma_f32_32x32x16_f16 v[16:31], v[40:43], v[210:213], v[16:31]
	v_fma_f32 v243, v2, v118, v243
	v_fma_f32 v244, v3, v119, v244
	v_max_i32_e32 v4, 0, v4
	v_max_i32_e32 v5, 0, v5
	v_fma_f32 v243, v4, v120, v243
	v_fma_f32 v244, v5, v121, v244
	s_waitcnt lgkmcnt(13)
	v_mfma_f32_32x32x16_f16 v[16:31], v[44:47], v[214:217], v[16:31]
	v_max_i32_e32 v6, 0, v6
	v_max_i32_e32 v7, 0, v7
	v_fma_f32 v243, v6, v122, v243
	v_fma_f32 v244, v7, v123, v244
	v_max_i32_e32 v8, 0, v8
	s_waitcnt lgkmcnt(12)
	v_mfma_f32_32x32x16_f16 v[16:31], v[48:51], v[218:221], v[16:31]
	v_max_i32_e32 v9, 0, v9
	v_fma_f32 v243, v8, v124, v243
	v_fma_f32 v244, v9, v125, v244
	v_max_i32_e32 v10, 0, v10
	v_max_i32_e32 v11, 0, v11
	s_waitcnt lgkmcnt(11)
	v_mfma_f32_32x32x16_f16 v[16:31], v[52:55], v[222:225], v[16:31]
	v_fma_f32 v243, v10, v126, v243
	v_fma_f32 v244, v11, v127, v244
	v_max_i32_e32 v12, 0, v12
	v_max_i32_e32 v13, 0, v13
	v_fma_f32 v243, v12, v128, v243
	s_waitcnt lgkmcnt(10)
	v_mfma_f32_32x32x16_f16 v[16:31], v[56:59], v[226:229], v[16:31]
	v_fma_f32 v244, v13, v129, v244
	v_max_i32_e32 v14, 0, v14
	v_max_i32_e32 v15, 0, v15
	v_fma_f32 v243, v14, v130, v243
	v_fma_f32 v244, v15, v131, v244
	s_waitcnt lgkmcnt(9)
	v_mfma_f32_32x32x16_f16 v[16:31], v[60:63], v[230:233], v[16:31]
	v_add_f32_e32 v245, v243, v244
	v_mov_b32_e32 v246, v245
	v_lshlrev_b32_e32 v247, 2, v32
	s_nop 0
	v_permlane32_swap_b32_e32 v246, v245
	s_waitcnt lgkmcnt(8)
	v_mfma_f32_32x32x16_f16 v[16:31], v[64:67], v[234:237], v[16:31]
	v_add_f32_e32 v246, v246, v245
	s_mov_b64 exec, s[4:5]
	global_store_dword v247, v246, s[8:9] offset:128
	s_mov_b64 exec, -1
	s_branch .Lp11_join5

; #define LAS __attribute__((address_space(3)))
; DI void indexer_tile(const LAS unsigned char* buf, const f16x8 (&af)[2][8], const f32x4 (&wv)[2][4], float* sc0, float* sc1, int kt, int r32, int h2) {
;     ...
;     f16x8 bfr[2][8];
; #pragma unroll
;     for (int sub = 0; sub < 2; ++sub)
; #pragma unroll
;         for (int ks = 0; ks < 8; ++ks) bfr[sub][ks] = *(const LAS f16x8*)(buf + (32 * sub + r32) * KT_ROWB + (16 * ks + 8 * h2) * 2);
;     __builtin_amdgcn_sched_barrier(0);
; #pragma unroll
;     for (int sub = 0; sub < 2; ++sub) {
;         f32x16 c0, c1;
; #pragma unroll
;         for (int i = 0; i < 16; ++i) { c0[i] = 0.f; c1[i] = 0.f; }
; #pragma unroll
;         for (int ks = 0; ks < 8; ++ks) { c0 = __builtin_amdgcn_mfma_f32_32x32x16_f16(af[0][ks], bfr[sub][ks], c0, 0, 0, 0); c1 = __builtin_amdgcn_mfma_f32_32x32x16_f16(af[1][ks], bfr[sub][ks], c1, 0, 0, 0); }
;         f32x2_t a0 = {0.f, 0.f}, a1 = {0.f, 0.f};
; #pragma unroll
;         for (int q = 0; q < 4; ++q)
; #pragma unroll
;             for (int e = 0; e < 4; e += 2) {
;                 const f32x2_t r0 = {relu1(c0[4 * q + e]), relu1(c0[4 * q + e + 1])};
;                 const f32x2_t r1 = {relu1(c1[4 * q + e]), relu1(c1[4 * q + e + 1])};
;                 const f32x2_t w0 = {wv[0][q][e], wv[0][q][e + 1]}, w1 = {wv[1][q][e], wv[1][q][e + 1]};
;                 a0 = __builtin_elementwise_fma(r0, w0, a0); a1 = __builtin_elementwise_fma(r1, w1, a1); }
;         float s0 = a0.x + a0.y, s1 = a1.x + a1.y;
;         s0 += __shfl_xor(s0, 32); s1 += __shfl_xor(s1, 32);
;         if (h2 == 0) { sc0[kt * 64 + 32 * sub + r32] = s0; sc1[kt * 64 + 32 * sub + r32] = s1; }
;     }
; DI void indexer_phase(const unsigned short* QI, const unsigned short* KI16, const float* WI, float* SC, LAS unsigned char* lds, int tid, int bid, int G) {
;     ...
;                 if (kt + 2 < nt) { *(LAS u32x4*)(buf0 + key0 * KT_ROWB + ch * 16) = a0; *(LAS u32x4*)(buf0 + (key0 + 32) * KT_ROWB + ch * 16) = a1; }
;                 __syncthreads();
.Lp11_join5:
	v_mfma_f32_32x32x16_f16 v[0:15], v[84:87], v[250:253], 0
	v_mfma_f32_32x32x16_f16 v[0:15], v[88:91], v[210:213], v[0:15]
	v_mfma_f32_32x32x16_f16 v[0:15], v[92:95], v[214:217], v[0:15]
	s_nop 8
	v_max_i32_e32 v16, 0, v16
	v_max_i32_e32 v17, 0, v17
	v_fma_f32 v238, v16, v68, 0
	v_fma_f32 v239, v17, v69, 0
	v_max_i32_e32 v18, 0, v18
	v_max_i32_e32 v19, 0, v19
	v_fma_f32 v238, v18, v70, v238
	v_mfma_f32_32x32x16_f16 v[0:15], v[96:99], v[218:221], v[0:15]
	v_fma_f32 v239, v19, v71, v239
	v_max_i32_e32 v20, 0, v20
	v_max_i32_e32 v21, 0, v21
	v_fma_f32 v238, v20, v72, v238
	v_fma_f32 v239, v21, v73, v239
	v_max_i32_e32 v22, 0, v22
	v_max_i32_e32 v23, 0, v23
	v_mfma_f32_32x32x16_f16 v[0:15], v[100:103], v[222:225], v[0:15]
	v_fma_f32 v238, v22, v74, v238
	v_fma_f32 v239, v23, v75, v239
	v_max_i32_e32 v24, 0, v24
	v_max_i32_e32 v25, 0, v25
	v_fma_f32 v238, v24, v76, v238
	v_fma_f32 v239, v25, v77, v239
	v_mfma_f32_32x32x16_f16 v[0:15], v[104:107], v[226:229], v[0:15]
	v_max_i32_e32 v26, 0, v26
	v_max_i32_e32 v27, 0, v27
	v_fma_f32 v238, v26, v78, v238
	v_fma_f32 v239, v27, v79, v239
	v_max_i32_e32 v28, 0, v28
	v_max_i32_e32 v29, 0, v29
	v_mfma_f32_32x32x16_f16 v[0:15], v[108:111], v[230:233], v[0:15]
	v_fma_f32 v238, v28, v80, v238
	v_fma_f32 v239, v29, v81, v239
	v_max_i32_e32 v30, 0, v30
	v_max_i32_e32 v31, 0, v31
	v_fma_f32 v238, v30, v82, v238
	v_fma_f32 v239, v31, v83, v239
	v_mfma_f32_32x32x16_f16 v[0:15], v[112:115], v[234:237], v[0:15]
	v_add_f32_e32 v240, v238, v239
	v_mov_b32_e32 v241, v240
	v_lshlrev_b32_e32 v242, 2, v32
	s_nop 0
	v_permlane32_swap_b32_e32 v241, v240
	v_add_f32_e32 v241, v241, v240
	s_mov_b64 exec, s[4:5]
	global_store_dword v242, v241, s[6:7] offset:256
	s_mov_b64 exec, -1
	s_waitcnt lgkmcnt(0)
	v_mfma_f32_32x32x16_f16 v[16:31], v[36:39], v[176:179], 0
	v_mfma_f32_32x32x16_f16 v[16:31], v[40:43], v[172:175], v[16:31]
	v_mfma_f32_32x32x16_f16 v[16:31], v[44:47], v[168:171], v[16:31]
	s_nop 8
	v_max_i32_e32 v0, 0, v0
	v_max_i32_e32 v1, 0, v1
	v_fma_f32 v243, v0, v116, 0
	v_fma_f32 v244, v1, v117, 0
	v_max_i32_e32 v2, 0, v2
	v_max_i32_e32 v3, 0, v3
	v_fma_f32 v243, v2, v118, v243
	v_mfma_f32_32x32x16_f16 v[16:31], v[48:51], v[164:167], v[16:31]
	v_fma_f32 v244, v3, v119, v244
	v_max_i32_e32 v4, 0, v4
	v_max_i32_e32 v5, 0, v5
	v_fma_f32 v243, v4, v120, v243
	v_fma_f32 v244, v5, v121, v244
	v_max_i32_e32 v6, 0, v6
	v_max_i32_e32 v7, 0, v7
	v_mfma_f32_32x32x16_f16 v[16:31], v[52:55], v[160:163], v[16:31]
	v_fma_f32 v243, v6, v122, v243
	v_fma_f32 v244, v7, v123, v244
	v_max_i32_e32 v8, 0, v8
	v_max_i32_e32 v9, 0, v9
	v_fma_f32 v243, v8, v124, v243
	v_fma_f32 v244, v9, v125, v244
	v_mfma_f32_32x32x16_f16 v[16:31], v[56:59], v[156:159], v[16:31]
	v_max_i32_e32 v10, 0, v10
	v_max_i32_e32 v11, 0, v11
	v_fma_f32 v243, v10, v126, v243
	v_fma_f32 v244, v11, v127, v244
	v_max_i32_e32 v12, 0, v12
	v_max_i32_e32 v13, 0, v13
	v_mfma_f32_32x32x16_f16 v[16:31], v[60:63], v[152:155], v[16:31]
	v_fma_f32 v243, v12, v128, v243
	v_fma_f32 v244, v13, v129, v244
	v_max_i32_e32 v14, 0, v14
	v_max_i32_e32 v15, 0, v15
	v_fma_f32 v243, v14, v130, v243
	v_fma_f32 v244, v15, v131, v244
	v_mfma_f32_32x32x16_f16 v[16:31], v[64:67], v[148:151], v[16:31]
	v_add_f32_e32 v245, v243, v244
	v_mov_b32_e32 v246, v245
	v_lshlrev_b32_e32 v247, 2, v32
	s_nop 0
	v_permlane32_swap_b32_e32 v246, v245
	v_add_f32_e32 v246, v246, v245
	s_mov_b64 exec, s[4:5]
	global_store_dword v247, v246, s[8:9] offset:256
	s_mov_b64 exec, -1
	v_mfma_f32_32x32x16_f16 v[0:15], v[84:87], v[176:179], 0
	v_mfma_f32_32x32x16_f16 v[0:15], v[88:91], v[172:175], v[0:15]
	v_mfma_f32_32x32x16_f16 v[0:15], v[92:95], v[168:171], v[0:15]
	s_nop 8
	v_max_i32_e32 v16, 0, v16
	v_max_i32_e32 v17, 0, v17
	v_fma_f32 v238, v16, v68, 0
	v_fma_f32 v239, v17, v69, 0
	v_max_i32_e32 v18, 0, v18
	v_max_i32_e32 v19, 0, v19
	v_fma_f32 v238, v18, v70, v238
	v_mfma_f32_32x32x16_f16 v[0:15], v[96:99], v[164:167], v[0:15]
	v_fma_f32 v239, v19, v71, v239
	v_max_i32_e32 v20, 0, v20
	v_max_i32_e32 v21, 0, v21
	v_fma_f32 v238, v20, v72, v238
	v_fma_f32 v239, v21, v73, v239
	v_max_i32_e32 v22, 0, v22
	v_max_i32_e32 v23, 0, v23
	v_mfma_f32_32x32x16_f16 v[0:15], v[100:103], v[160:163], v[0:15]
	v_fma_f32 v238, v22, v74, v238
	v_fma_f32 v239, v23, v75, v239
	v_max_i32_e32 v24, 0, v24
	v_max_i32_e32 v25, 0, v25
	v_fma_f32 v238, v24, v76, v238
	v_fma_f32 v239, v25, v77, v239
	v_mfma_f32_32x32x16_f16 v[0:15], v[104:107], v[156:159], v[0:15]
	v_max_i32_e32 v26, 0, v26
	v_max_i32_e32 v27, 0, v27
	v_fma_f32 v238, v26, v78, v238
	v_fma_f32 v239, v27, v79, v239
	v_max_i32_e32 v28, 0, v28
	v_max_i32_e32 v29, 0, v29
	v_mfma_f32_32x32x16_f16 v[0:15], v[108:111], v[152:155], v[0:15]
	v_fma_f32 v238, v28, v80, v238
	v_fma_f32 v239, v29, v81, v239
	v_max_i32_e32 v30, 0, v30
	v_max_i32_e32 v31, 0, v31
	v_fma_f32 v238, v30, v82, v238
	v_fma_f32 v239, v31, v83, v239
	v_mfma_f32_32x32x16_f16 v[0:15], v[112:115], v[148:151], v[0:15]
	v_add_f32_e32 v240, v238, v239
	v_mov_b32_e32 v241, v240
	v_lshlrev_b32_e32 v242, 2, v32
	s_nop 0
	v_permlane32_swap_b32_e32 v241, v240
	v_add_f32_e32 v241, v241, v240
	s_mov_b64 exec, s[4:5]
	global_store_dword v242, v241, s[6:7] offset:384
	s_mov_b64 exec, -1
	s_mov_b32 s98, 1
	s_andn2_b64 vcc, exec, s[10:11]
	s_cbranch_vccnz .LBB0_1868
	s_waitcnt vmcnt(7)
	ds_write_b128 v209, v[132:135]
	ds_write_b128 v209, v[136:139] offset:8704
	s_branch .LBB0_1868

; #define LAS __attribute__((address_space(3)))
; DI void indexer_tile(const LAS unsigned char* buf, const f16x8 (&af)[2][8], const f32x4 (&wv)[2][4], float* sc0, float* sc1, int kt, int r32, int h2) {
;     ...
;     f16x8 bfr[2][8];
; #pragma unroll
;     for (int sub = 0; sub < 2; ++sub)
; #pragma unroll
;         for (int ks = 0; ks < 8; ++ks) bfr[sub][ks] = *(const LAS f16x8*)(buf + (32 * sub + r32) * KT_ROWB + (16 * ks + 8 * h2) * 2);
;     __builtin_amdgcn_sched_barrier(0);
; #pragma unroll
;     for (int sub = 0; sub < 2; ++sub) {
;         f32x16 c0, c1;
; #pragma unroll
;         for (int i = 0; i < 16; ++i) { c0[i] = 0.f; c1[i] = 0.f; }
; #pragma unroll
;         for (int ks = 0; ks < 8; ++ks) { c0 = __builtin_amdgcn_mfma_f32_32x32x16_f16(af[0][ks], bfr[sub][ks], c0, 0, 0, 0); c1 = __builtin_amdgcn_mfma_f32_32x32x16_f16(af[1][ks], bfr[sub][ks], c1, 0, 0, 0); }
;         f32x2_t a0 = {0.f, 0.f}, a1 = {0.f, 0.f};
; #pragma unroll
;         for (int q = 0; q < 4; ++q)
; #pragma unroll
;             for (int e = 0; e < 4; e += 2) {
;                 const f32x2_t r0 = {relu1(c0[4 * q + e]), relu1(c0[4 * q + e + 1])};
;                 const f32x2_t r1 = {relu1(c1[4 * q + e]), relu1(c1[4 * q + e + 1])};
;                 const f32x2_t w0 = {wv[0][q][e], wv[0][q][e + 1]}, w1 = {wv[1][q][e], wv[1][q][e + 1]};
;                 a0 = __builtin_elementwise_fma(r0, w0, a0); a1 = __builtin_elementwise_fma(r1, w1, a1); }
;         float s0 = a0.x + a0.y, s1 = a1.x + a1.y;
;         s0 += __shfl_xor(s0, 32); s1 += __shfl_xor(s1, 32);
;         if (h2 == 0) { sc0[kt * 64 + 32 * sub + r32] = s0; sc1[kt * 64 + 32 * sub + r32] = s1; }
;     }
; DI void indexer_phase(const unsigned short* QI, const unsigned short* KI16, const float* WI, float* SC, LAS unsigned char* lds, int tid, int bid, int G) {
;     ...
;             for (int kt = 0; kt < nt; kt += 2) {
;                 if (kt + 2 < nt) { const unsigned short* p = src + (size_t)(kt + 2) * 64 * 128; a0 = *(const u32x4*)p; a1 = *(const u32x4*)(p + 32 * 128); }
;                 indexer_tile(buf0, af, wv, sc0, sc1, kt, r32, h2);
.LBB0_1891:
	ds_read_b128 v[250:253], v207
	ds_read_b128 v[210:213], v207 offset:32
	ds_read_b128 v[214:217], v207 offset:64
	ds_read_b128 v[218:221], v207 offset:96
	ds_read_b128 v[222:225], v207 offset:128
	ds_read_b128 v[226:229], v207 offset:160
	ds_read_b128 v[230:233], v207 offset:192
	ds_read_b128 v[234:237], v207 offset:224
	ds_read_b128 v[174:177], v207 offset:8704
	ds_read_b128 v[170:173], v207 offset:8736
	ds_read_b128 v[166:169], v207 offset:8768
	ds_read_b128 v[162:165], v207 offset:8800
	ds_read_b128 v[158:161], v207 offset:8832
	ds_read_b128 v[154:157], v207 offset:8864
	ds_read_b128 v[150:153], v207 offset:8896
	ds_read_b128 v[146:149], v207 offset:8928
	s_cmp_eq_u32 s98, 0
	s_cbranch_scc1 .Lp11_plain6
	s_waitcnt lgkmcnt(15)
	v_mfma_f32_32x32x16_f16 v[16:31], v[34:37], v[250:253], 0
	v_max_i32_e32 v0, 0, v0
	v_max_i32_e32 v1, 0, v1
	v_fma_f32 v243, v0, v114, 0
	v_fma_f32 v244, v1, v115, 0
	v_max_i32_e32 v2, 0, v2
	v_max_i32_e32 v3, 0, v3
	s_waitcnt lgkmcnt(14)
	v_mfma_f32_32x32x16_f16 v[16:31], v[38:41], v[210:213], v[16:31]
	v_fma_f32 v243, v2, v116, v243
	v_fma_f32 v244, v3, v117, v244
	v_max_i32_e32 v4, 0, v4
	v_max_i32_e32 v5, 0, v5
	v_fma_f32 v243, v4, v118, v243
	v_fma_f32 v244, v5, v119, v244
	s_waitcnt lgkmcnt(13)
	v_mfma_f32_32x32x16_f16 v[16:31], v[42:45], v[214:217], v[16:31]
	v_max_i32_e32 v6, 0, v6
	v_max_i32_e32 v7, 0, v7
	v_fma_f32 v243, v6, v120, v243
	v_fma_f32 v244, v7, v121, v244
	v_max_i32_e32 v8, 0, v8
	s_waitcnt lgkmcnt(12)
	v_mfma_f32_32x32x16_f16 v[16:31], v[46:49], v[218:221], v[16:31]
	v_max_i32_e32 v9, 0, v9
	v_fma_f32 v243, v8, v122, v243
	v_fma_f32 v244, v9, v123, v244
	v_max_i32_e32 v10, 0, v10
	v_max_i32_e32 v11, 0, v11
	s_waitcnt lgkmcnt(11)
	v_mfma_f32_32x32x16_f16 v[16:31], v[50:53], v[222:225], v[16:31]
	v_fma_f32 v243, v10, v124, v243
	v_fma_f32 v244, v11, v125, v244
	v_max_i32_e32 v12, 0, v12
	v_max_i32_e32 v13, 0, v13
	v_fma_f32 v243, v12, v126, v243
	s_waitcnt lgkmcnt(10)
	v_mfma_f32_32x32x16_f16 v[16:31], v[54:57], v[226:229], v[16:31]
	v_fma_f32 v244, v13, v127, v244
	v_max_i32_e32 v14, 0, v14
	v_max_i32_e32 v15, 0, v15
	v_fma_f32 v243, v14, v128, v243
	v_fma_f32 v244, v15, v129, v244
	s_waitcnt lgkmcnt(9)
	v_mfma_f32_32x32x16_f16 v[16:31], v[58:61], v[230:233], v[16:31]
	v_add_f32_e32 v245, v243, v244
	v_mov_b32_e32 v246, v245
	v_lshlrev_b32_e32 v247, 2, v32
	s_nop 0
	v_permlane32_swap_b32_e32 v246, v245
	s_waitcnt lgkmcnt(8)
	v_mfma_f32_32x32x16_f16 v[16:31], v[62:65], v[234:237], v[16:31]
	v_add_f32_e32 v246, v246, v245
	s_mov_b64 exec, s[4:5]
	global_store_dword v247, v246, s[8:9] offset:-128
	s_mov_b64 exec, -1
	s_branch .Lp11_join6

; #define LAS __attribute__((address_space(3)))
; DI void indexer_tile(const LAS unsigned char* buf, const f16x8 (&af)[2][8], const f32x4 (&wv)[2][4], float* sc0, float* sc1, int kt, int r32, int h2) {
;     ...
;     f16x8 bfr[2][8];
; #pragma unroll
;     for (int sub = 0; sub < 2; ++sub)
; #pragma unroll
;         for (int ks = 0; ks < 8; ++ks) bfr[sub][ks] = *(const LAS f16x8*)(buf + (32 * sub + r32) * KT_ROWB + (16 * ks + 8 * h2) * 2);
;     __builtin_amdgcn_sched_barrier(0);
; #pragma unroll
;     for (int sub = 0; sub < 2; ++sub) {
;         f32x16 c0, c1;
; #pragma unroll
;         for (int i = 0; i < 16; ++i) { c0[i] = 0.f; c1[i] = 0.f; }
; #pragma unroll
;         for (int ks = 0; ks < 8; ++ks) { c0 = __builtin_amdgcn_mfma_f32_32x32x16_f16(af[0][ks], bfr[sub][ks], c0, 0, 0, 0); c1 = __builtin_amdgcn_mfma_f32_32x32x16_f16(af[1][ks], bfr[sub][ks], c1, 0, 0, 0); }
;         f32x2_t a0 = {0.f, 0.f}, a1 = {0.f, 0.f};
; #pragma unroll
;         for (int q = 0; q < 4; ++q)
; #pragma unroll
;             for (int e = 0; e < 4; e += 2) {
;                 const f32x2_t r0 = {relu1(c0[4 * q + e]), relu1(c0[4 * q + e + 1])};
;                 const f32x2_t r1 = {relu1(c1[4 * q + e]), relu1(c1[4 * q + e + 1])};
;                 const f32x2_t w0 = {wv[0][q][e], wv[0][q][e + 1]}, w1 = {wv[1][q][e], wv[1][q][e + 1]};
;                 a0 = __builtin_elementwise_fma(r0, w0, a0); a1 = __builtin_elementwise_fma(r1, w1, a1); }
;         float s0 = a0.x + a0.y, s1 = a1.x + a1.y;
;         s0 += __shfl_xor(s0, 32); s1 += __shfl_xor(s1, 32);
;         if (h2 == 0) { sc0[kt * 64 + 32 * sub + r32] = s0; sc1[kt * 64 + 32 * sub + r32] = s1; }
;     }
; DI void indexer_phase(const unsigned short* QI, const unsigned short* KI16, const float* WI, float* SC, LAS unsigned char* lds, int tid, int bid, int G) {
;     ...
;                 indexer_tile(buf0, af, wv, sc0, sc1, kt, r32, h2);
;                 if (kt + 1 < nt) { *(LAS u32x4*)(buf1 + key0 * KT_ROWB + ch * 16) = b0; *(LAS u32x4*)(buf1 + (key0 + 32) * KT_ROWB + ch * 16) = b1; }
.Lp11_join6:
	v_mfma_f32_32x32x16_f16 v[0:15], v[82:85], v[250:253], 0
	v_mfma_f32_32x32x16_f16 v[0:15], v[86:89], v[210:213], v[0:15]
	v_mfma_f32_32x32x16_f16 v[0:15], v[90:93], v[214:217], v[0:15]
	s_nop 8
	v_max_i32_e32 v16, 0, v16
	v_max_i32_e32 v17, 0, v17
	v_fma_f32 v238, v16, v66, 0
	v_fma_f32 v239, v17, v67, 0
	v_max_i32_e32 v18, 0, v18
	v_max_i32_e32 v19, 0, v19
	v_fma_f32 v238, v18, v68, v238
	v_mfma_f32_32x32x16_f16 v[0:15], v[94:97], v[218:221], v[0:15]
	v_fma_f32 v239, v19, v69, v239
	v_max_i32_e32 v20, 0, v20
	v_max_i32_e32 v21, 0, v21
	v_fma_f32 v238, v20, v70, v238
	v_fma_f32 v239, v21, v71, v239
	v_max_i32_e32 v22, 0, v22
	v_max_i32_e32 v23, 0, v23
	v_mfma_f32_32x32x16_f16 v[0:15], v[98:101], v[222:225], v[0:15]
	v_fma_f32 v238, v22, v72, v238
	v_fma_f32 v239, v23, v73, v239
	v_max_i32_e32 v24, 0, v24
	v_max_i32_e32 v25, 0, v25
	v_fma_f32 v238, v24, v74, v238
	v_fma_f32 v239, v25, v75, v239
	v_mfma_f32_32x32x16_f16 v[0:15], v[102:105], v[226:229], v[0:15]
	v_max_i32_e32 v26, 0, v26
	v_max_i32_e32 v27, 0, v27
	v_fma_f32 v238, v26, v76, v238
	v_fma_f32 v239, v27, v77, v239
	v_max_i32_e32 v28, 0, v28
	v_max_i32_e32 v29, 0, v29
	v_mfma_f32_32x32x16_f16 v[0:15], v[106:109], v[230:233], v[0:15]
	v_fma_f32 v238, v28, v78, v238
	v_fma_f32 v239, v29, v79, v239
	v_max_i32_e32 v30, 0, v30
	v_max_i32_e32 v31, 0, v31
	v_fma_f32 v238, v30, v80, v238
	v_fma_f32 v239, v31, v81, v239
	v_mfma_f32_32x32x16_f16 v[0:15], v[110:113], v[234:237], v[0:15]
	v_add_f32_e32 v240, v238, v239
	v_mov_b32_e32 v241, v240
	v_lshlrev_b32_e32 v242, 2, v32
	s_nop 0
	v_permlane32_swap_b32_e32 v241, v240
	v_add_f32_e32 v241, v241, v240
	s_mov_b64 exec, s[4:5]
	global_store_dword v242, v241, s[6:7]
	s_mov_b64 exec, -1
	s_waitcnt lgkmcnt(0)
	v_mfma_f32_32x32x16_f16 v[16:31], v[34:37], v[174:177], 0
	v_mfma_f32_32x32x16_f16 v[16:31], v[38:41], v[170:173], v[16:31]
	v_mfma_f32_32x32x16_f16 v[16:31], v[42:45], v[166:169], v[16:31]
	s_nop 8
	v_max_i32_e32 v0, 0, v0
	v_max_i32_e32 v1, 0, v1
	v_fma_f32 v243, v0, v114, 0
	v_fma_f32 v244, v1, v115, 0
	v_max_i32_e32 v2, 0, v2
	v_max_i32_e32 v3, 0, v3
	v_fma_f32 v243, v2, v116, v243
	v_mfma_f32_32x32x16_f16 v[16:31], v[46:49], v[162:165], v[16:31]
	v_fma_f32 v244, v3, v117, v244
	v_max_i32_e32 v4, 0, v4
	v_max_i32_e32 v5, 0, v5
	v_fma_f32 v243, v4, v118, v243
	v_fma_f32 v244, v5, v119, v244
	v_max_i32_e32 v6, 0, v6
	v_max_i32_e32 v7, 0, v7
	v_mfma_f32_32x32x16_f16 v[16:31], v[50:53], v[158:161], v[16:31]
	v_fma_f32 v243, v6, v120, v243
	v_fma_f32 v244, v7, v121, v244
	v_max_i32_e32 v8, 0, v8
	v_max_i32_e32 v9, 0, v9
	v_fma_f32 v243, v8, v122, v243
	v_fma_f32 v244, v9, v123, v244
	v_mfma_f32_32x32x16_f16 v[16:31], v[54:57], v[154:157], v[16:31]
	v_max_i32_e32 v10, 0, v10
	v_max_i32_e32 v11, 0, v11
	v_fma_f32 v243, v10, v124, v243
	v_fma_f32 v244, v11, v125, v244
	v_max_i32_e32 v12, 0, v12
	v_max_i32_e32 v13, 0, v13
	v_mfma_f32_32x32x16_f16 v[16:31], v[58:61], v[150:153], v[16:31]
	v_fma_f32 v243, v12, v126, v243
	v_fma_f32 v244, v13, v127, v244
	v_max_i32_e32 v14, 0, v14
	v_max_i32_e32 v15, 0, v15
	v_fma_f32 v243, v14, v128, v243
	v_fma_f32 v244, v15, v129, v244
	v_mfma_f32_32x32x16_f16 v[16:31], v[62:65], v[146:149], v[16:31]
	v_add_f32_e32 v245, v243, v244
	v_mov_b32_e32 v246, v245
	v_lshlrev_b32_e32 v247, 2, v32
	s_nop 0
	v_permlane32_swap_b32_e32 v246, v245
	v_add_f32_e32 v246, v246, v245
	s_mov_b64 exec, s[4:5]
	global_store_dword v247, v246, s[8:9]
	s_mov_b64 exec, -1
	v_mfma_f32_32x32x16_f16 v[0:15], v[82:85], v[174:177], 0
	v_mfma_f32_32x32x16_f16 v[0:15], v[86:89], v[170:173], v[0:15]
	v_mfma_f32_32x32x16_f16 v[0:15], v[90:93], v[166:169], v[0:15]
	s_nop 8
	v_max_i32_e32 v16, 0, v16
	v_max_i32_e32 v17, 0, v17
	v_fma_f32 v238, v16, v66, 0
	v_fma_f32 v239, v17, v67, 0
	v_max_i32_e32 v18, 0, v18
	v_max_i32_e32 v19, 0, v19
	v_fma_f32 v238, v18, v68, v238
	v_mfma_f32_32x32x16_f16 v[0:15], v[94:97], v[162:165], v[0:15]
	v_fma_f32 v239, v19, v69, v239
	v_max_i32_e32 v20, 0, v20
	v_max_i32_e32 v21, 0, v21
	v_fma_f32 v238, v20, v70, v238
	v_fma_f32 v239, v21, v71, v239
	v_max_i32_e32 v22, 0, v22
	v_max_i32_e32 v23, 0, v23
	v_mfma_f32_32x32x16_f16 v[0:15], v[98:101], v[158:161], v[0:15]
	v_fma_f32 v238, v22, v72, v238
	v_fma_f32 v239, v23, v73, v239
	v_max_i32_e32 v24, 0, v24
	v_max_i32_e32 v25, 0, v25
	v_fma_f32 v238, v24, v74, v238
	v_fma_f32 v239, v25, v75, v239
	v_mfma_f32_32x32x16_f16 v[0:15], v[102:105], v[154:157], v[0:15]
	v_max_i32_e32 v26, 0, v26
	v_max_i32_e32 v27, 0, v27
	v_fma_f32 v238, v26, v76, v238
	v_fma_f32 v239, v27, v77, v239
	v_max_i32_e32 v28, 0, v28
	v_max_i32_e32 v29, 0, v29
	v_mfma_f32_32x32x16_f16 v[0:15], v[106:109], v[150:153], v[0:15]
	v_fma_f32 v238, v28, v78, v238
	v_fma_f32 v239, v29, v79, v239
	v_max_i32_e32 v30, 0, v30
	v_max_i32_e32 v31, 0, v31
	v_fma_f32 v238, v30, v80, v238
	v_fma_f32 v239, v31, v81, v239
	v_mfma_f32_32x32x16_f16 v[0:15], v[110:113], v[146:149], v[0:15]
	v_add_f32_e32 v240, v238, v239
	v_mov_b32_e32 v241, v240
	v_lshlrev_b32_e32 v242, 2, v32
	s_nop 0
	v_permlane32_swap_b32_e32 v241, v240
	v_add_f32_e32 v241, v241, v240
	s_mov_b64 exec, s[4:5]
	global_store_dword v242, v241, s[6:7] offset:128
	s_mov_b64 exec, -1
	s_mov_b32 s98, 1
	s_add_i32 s18, s14, -3
	s_cmp_lt_u32 s18, s42
	s_cselect_b64 s[12:13], -1, 0
	s_cmp_ge_u32 s18, s42
	s_cbranch_scc1 .LBB0_1897
	s_waitcnt vmcnt(8)
	ds_write_b128 v209, v[134:137] offset:17408
	ds_write_b128 v209, v[142:145] offset:26112

; #define LAS __attribute__((address_space(3)))
; DI void indexer_tile(const LAS unsigned char* buf, const f16x8 (&af)[2][8], const f32x4 (&wv)[2][4], float* sc0, float* sc1, int kt, int r32, int h2) {
;     ...
;     f16x8 bfr[2][8];
; #pragma unroll
;     for (int sub = 0; sub < 2; ++sub)
; #pragma unroll
;         for (int ks = 0; ks < 8; ++ks) bfr[sub][ks] = *(const LAS f16x8*)(buf + (32 * sub + r32) * KT_ROWB + (16 * ks + 8 * h2) * 2);
;     __builtin_amdgcn_sched_barrier(0);
; #pragma unroll
;     for (int sub = 0; sub < 2; ++sub) {
;         f32x16 c0, c1;
; #pragma unroll
;         for (int i = 0; i < 16; ++i) { c0[i] = 0.f; c1[i] = 0.f; }
; #pragma unroll
;         for (int ks = 0; ks < 8; ++ks) { c0 = __builtin_amdgcn_mfma_f32_32x32x16_f16(af[0][ks], bfr[sub][ks], c0, 0, 0, 0); c1 = __builtin_amdgcn_mfma_f32_32x32x16_f16(af[1][ks], bfr[sub][ks], c1, 0, 0, 0); }
;         f32x2_t a0 = {0.f, 0.f}, a1 = {0.f, 0.f};
; #pragma unroll
;         for (int q = 0; q < 4; ++q)
; #pragma unroll
;             for (int e = 0; e < 4; e += 2) {
;                 const f32x2_t r0 = {relu1(c0[4 * q + e]), relu1(c0[4 * q + e + 1])};
;                 const f32x2_t r1 = {relu1(c1[4 * q + e]), relu1(c1[4 * q + e + 1])};
;                 const f32x2_t w0 = {wv[0][q][e], wv[0][q][e + 1]}, w1 = {wv[1][q][e], wv[1][q][e + 1]};
;                 a0 = __builtin_elementwise_fma(r0, w0, a0); a1 = __builtin_elementwise_fma(r1, w1, a1); }
;         float s0 = a0.x + a0.y, s1 = a1.x + a1.y;
;         s0 += __shfl_xor(s0, 32); s1 += __shfl_xor(s1, 32);
;         if (h2 == 0) { sc0[kt * 64 + 32 * sub + r32] = s0; sc1[kt * 64 + 32 * sub + r32] = s1; }
;     }
; DI void indexer_phase(const unsigned short* QI, const unsigned short* KI16, const float* WI, float* SC, LAS unsigned char* lds, int tid, int bid, int G) {
;     ...
;                 if (kt + 3 < nt) { const unsigned short* p = src + (size_t)(kt + 3) * 64 * 128; b0 = *(const u32x4*)p; b1 = *(const u32x4*)(p + 32 * 128); }
;                 indexer_tile(buf1, af, wv, sc0, sc1, kt + 1, r32, h2);
.LBB0_1900:
	ds_read_b128 v[250:253], v207 offset:17408
	ds_read_b128 v[210:213], v207 offset:17440
	ds_read_b128 v[214:217], v207 offset:17472
	ds_read_b128 v[218:221], v207 offset:17504
	ds_read_b128 v[222:225], v207 offset:17536
	ds_read_b128 v[226:229], v207 offset:17568
	ds_read_b128 v[230:233], v207 offset:17600
	ds_read_b128 v[234:237], v207 offset:17632
	ds_read_b128 v[174:177], v207 offset:26112
	ds_read_b128 v[170:173], v207 offset:26144
	ds_read_b128 v[166:169], v207 offset:26176
	ds_read_b128 v[162:165], v207 offset:26208
	ds_read_b128 v[158:161], v207 offset:26240
	ds_read_b128 v[154:157], v207 offset:26272
	ds_read_b128 v[150:153], v207 offset:26304
	ds_read_b128 v[146:149], v207 offset:26336
	s_cmp_eq_u32 s98, 0
	s_cbranch_scc1 .Lp11_plain7
	s_waitcnt lgkmcnt(15)
	v_mfma_f32_32x32x16_f16 v[16:31], v[34:37], v[250:253], 0
	v_max_i32_e32 v0, 0, v0
	v_max_i32_e32 v1, 0, v1
	v_fma_f32 v243, v0, v114, 0
	v_fma_f32 v244, v1, v115, 0
	v_max_i32_e32 v2, 0, v2
	v_max_i32_e32 v3, 0, v3
	s_waitcnt lgkmcnt(14)
	v_mfma_f32_32x32x16_f16 v[16:31], v[38:41], v[210:213], v[16:31]
	v_fma_f32 v243, v2, v116, v243
	v_fma_f32 v244, v3, v117, v244
	v_max_i32_e32 v4, 0, v4
	v_max_i32_e32 v5, 0, v5
	v_fma_f32 v243, v4, v118, v243
	v_fma_f32 v244, v5, v119, v244
	s_waitcnt lgkmcnt(13)
	v_mfma_f32_32x32x16_f16 v[16:31], v[42:45], v[214:217], v[16:31]
	v_max_i32_e32 v6, 0, v6
	v_max_i32_e32 v7, 0, v7
	v_fma_f32 v243, v6, v120, v243
	v_fma_f32 v244, v7, v121, v244
	v_max_i32_e32 v8, 0, v8
	s_waitcnt lgkmcnt(12)
	v_mfma_f32_32x32x16_f16 v[16:31], v[46:49], v[218:221], v[16:31]
	v_max_i32_e32 v9, 0, v9
	v_fma_f32 v243, v8, v122, v243
	v_fma_f32 v244, v9, v123, v244
	v_max_i32_e32 v10, 0, v10
	v_max_i32_e32 v11, 0, v11
	s_waitcnt lgkmcnt(11)
	v_mfma_f32_32x32x16_f16 v[16:31], v[50:53], v[222:225], v[16:31]
	v_fma_f32 v243, v10, v124, v243
	v_fma_f32 v244, v11, v125, v244
	v_max_i32_e32 v12, 0, v12
	v_max_i32_e32 v13, 0, v13
	v_fma_f32 v243, v12, v126, v243
	s_waitcnt lgkmcnt(10)
	v_mfma_f32_32x32x16_f16 v[16:31], v[54:57], v[226:229], v[16:31]
	v_fma_f32 v244, v13, v127, v244
	v_max_i32_e32 v14, 0, v14
	v_max_i32_e32 v15, 0, v15
	v_fma_f32 v243, v14, v128, v243
	v_fma_f32 v244, v15, v129, v244
	s_waitcnt lgkmcnt(9)
	v_mfma_f32_32x32x16_f16 v[16:31], v[58:61], v[230:233], v[16:31]
	v_add_f32_e32 v245, v243, v244
	v_mov_b32_e32 v246, v245
	v_lshlrev_b32_e32 v247, 2, v32
	s_nop 0
	v_permlane32_swap_b32_e32 v246, v245
	s_waitcnt lgkmcnt(8)
	v_mfma_f32_32x32x16_f16 v[16:31], v[62:65], v[234:237], v[16:31]
	v_add_f32_e32 v246, v246, v245
	s_mov_b64 exec, s[4:5]
	global_store_dword v247, v246, s[8:9] offset:128
	s_mov_b64 exec, -1
	s_branch .Lp11_join7

; #define LAS __attribute__((address_space(3)))
; DI void indexer_tile(const LAS unsigned char* buf, const f16x8 (&af)[2][8], const f32x4 (&wv)[2][4], float* sc0, float* sc1, int kt, int r32, int h2) {
;     ...
;     f16x8 bfr[2][8];
; #pragma unroll
;     for (int sub = 0; sub < 2; ++sub)
; #pragma unroll
;         for (int ks = 0; ks < 8; ++ks) bfr[sub][ks] = *(const LAS f16x8*)(buf + (32 * sub + r32) * KT_ROWB + (16 * ks + 8 * h2) * 2);
;     __builtin_amdgcn_sched_barrier(0);
; #pragma unroll
;     for (int sub = 0; sub < 2; ++sub) {
;         f32x16 c0, c1;
; #pragma unroll
;         for (int i = 0; i < 16; ++i) { c0[i] = 0.f; c1[i] = 0.f; }
; #pragma unroll
;         for (int ks = 0; ks < 8; ++ks) { c0 = __builtin_amdgcn_mfma_f32_32x32x16_f16(af[0][ks], bfr[sub][ks], c0, 0, 0, 0); c1 = __builtin_amdgcn_mfma_f32_32x32x16_f16(af[1][ks], bfr[sub][ks], c1, 0, 0, 0); }
;         f32x2_t a0 = {0.f, 0.f}, a1 = {0.f, 0.f};
; #pragma unroll
;         for (int q = 0; q < 4; ++q)
; #pragma unroll
;             for (int e = 0; e < 4; e += 2) {
;                 const f32x2_t r0 = {relu1(c0[4 * q + e]), relu1(c0[4 * q + e + 1])};
;                 const f32x2_t r1 = {relu1(c1[4 * q + e]), relu1(c1[4 * q + e + 1])};
;                 const f32x2_t w0 = {wv[0][q][e], wv[0][q][e + 1]}, w1 = {wv[1][q][e], wv[1][q][e + 1]};
;                 a0 = __builtin_elementwise_fma(r0, w0, a0); a1 = __builtin_elementwise_fma(r1, w1, a1); }
;         float s0 = a0.x + a0.y, s1 = a1.x + a1.y;
;         s0 += __shfl_xor(s0, 32); s1 += __shfl_xor(s1, 32);
;         if (h2 == 0) { sc0[kt * 64 + 32 * sub + r32] = s0; sc1[kt * 64 + 32 * sub + r32] = s1; }
;     }
; DI void indexer_phase(const unsigned short* QI, const unsigned short* KI16, const float* WI, float* SC, LAS unsigned char* lds, int tid, int bid, int G) {
;     ...
;                 if (kt + 2 < nt) { *(LAS u32x4*)(buf0 + key0 * KT_ROWB + ch * 16) = a0; *(LAS u32x4*)(buf0 + (key0 + 32) * KT_ROWB + ch * 16) = a1; }
;                 __syncthreads();
.Lp11_join7:
	v_mfma_f32_32x32x16_f16 v[0:15], v[82:85], v[250:253], 0
	v_mfma_f32_32x32x16_f16 v[0:15], v[86:89], v[210:213], v[0:15]
	v_mfma_f32_32x32x16_f16 v[0:15], v[90:93], v[214:217], v[0:15]
	s_nop 8
	v_max_i32_e32 v16, 0, v16
	v_max_i32_e32 v17, 0, v17
	v_fma_f32 v238, v16, v66, 0
	v_fma_f32 v239, v17, v67, 0
	v_max_i32_e32 v18, 0, v18
	v_max_i32_e32 v19, 0, v19
	v_fma_f32 v238, v18, v68, v238
	v_mfma_f32_32x32x16_f16 v[0:15], v[94:97], v[218:221], v[0:15]
	v_fma_f32 v239, v19, v69, v239
	v_max_i32_e32 v20, 0, v20
	v_max_i32_e32 v21, 0, v21
	v_fma_f32 v238, v20, v70, v238
	v_fma_f32 v239, v21, v71, v239
	v_max_i32_e32 v22, 0, v22
	v_max_i32_e32 v23, 0, v23
	v_mfma_f32_32x32x16_f16 v[0:15], v[98:101], v[222:225], v[0:15]
	v_fma_f32 v238, v22, v72, v238
	v_fma_f32 v239, v23, v73, v239
	v_max_i32_e32 v24, 0, v24
	v_max_i32_e32 v25, 0, v25
	v_fma_f32 v238, v24, v74, v238
	v_fma_f32 v239, v25, v75, v239
	v_mfma_f32_32x32x16_f16 v[0:15], v[102:105], v[226:229], v[0:15]
	v_max_i32_e32 v26, 0, v26
	v_max_i32_e32 v27, 0, v27
	v_fma_f32 v238, v26, v76, v238
	v_fma_f32 v239, v27, v77, v239
	v_max_i32_e32 v28, 0, v28
	v_max_i32_e32 v29, 0, v29
	v_mfma_f32_32x32x16_f16 v[0:15], v[106:109], v[230:233], v[0:15]
	v_fma_f32 v238, v28, v78, v238
	v_fma_f32 v239, v29, v79, v239
	v_max_i32_e32 v30, 0, v30
	v_max_i32_e32 v31, 0, v31
	v_fma_f32 v238, v30, v80, v238
	v_fma_f32 v239, v31, v81, v239
	v_mfma_f32_32x32x16_f16 v[0:15], v[110:113], v[234:237], v[0:15]
	v_add_f32_e32 v240, v238, v239
	v_mov_b32_e32 v241, v240
	v_lshlrev_b32_e32 v242, 2, v32
	s_nop 0
	v_permlane32_swap_b32_e32 v241, v240
	v_add_f32_e32 v241, v241, v240
	s_mov_b64 exec, s[4:5]
	global_store_dword v242, v241, s[6:7] offset:256
	s_mov_b64 exec, -1
	s_waitcnt lgkmcnt(0)
	v_mfma_f32_32x32x16_f16 v[16:31], v[34:37], v[174:177], 0
	v_mfma_f32_32x32x16_f16 v[16:31], v[38:41], v[170:173], v[16:31]
	v_mfma_f32_32x32x16_f16 v[16:31], v[42:45], v[166:169], v[16:31]
	s_nop 8
	v_max_i32_e32 v0, 0, v0
	v_max_i32_e32 v1, 0, v1
	v_fma_f32 v243, v0, v114, 0
	v_fma_f32 v244, v1, v115, 0
	v_max_i32_e32 v2, 0, v2
	v_max_i32_e32 v3, 0, v3
	v_fma_f32 v243, v2, v116, v243
	v_mfma_f32_32x32x16_f16 v[16:31], v[46:49], v[162:165], v[16:31]
	v_fma_f32 v244, v3, v117, v244
	v_max_i32_e32 v4, 0, v4
	v_max_i32_e32 v5, 0, v5
	v_fma_f32 v243, v4, v118, v243
	v_fma_f32 v244, v5, v119, v244
	v_max_i32_e32 v6, 0, v6
	v_max_i32_e32 v7, 0, v7
	v_mfma_f32_32x32x16_f16 v[16:31], v[50:53], v[158:161], v[16:31]
	v_fma_f32 v243, v6, v120, v243
	v_fma_f32 v244, v7, v121, v244
	v_max_i32_e32 v8, 0, v8
	v_max_i32_e32 v9, 0, v9
	v_fma_f32 v243, v8, v122, v243
	v_fma_f32 v244, v9, v123, v244
	v_mfma_f32_32x32x16_f16 v[16:31], v[54:57], v[154:157], v[16:31]
	v_max_i32_e32 v10, 0, v10
	v_max_i32_e32 v11, 0, v11
	v_fma_f32 v243, v10, v124, v243
	v_fma_f32 v244, v11, v125, v244
	v_max_i32_e32 v12, 0, v12
	v_max_i32_e32 v13, 0, v13
	v_mfma_f32_32x32x16_f16 v[16:31], v[58:61], v[150:153], v[16:31]
	v_fma_f32 v243, v12, v126, v243
	v_fma_f32 v244, v13, v127, v244
	v_max_i32_e32 v14, 0, v14
	v_max_i32_e32 v15, 0, v15
	v_fma_f32 v243, v14, v128, v243
	v_fma_f32 v244, v15, v129, v244
	v_mfma_f32_32x32x16_f16 v[16:31], v[62:65], v[146:149], v[16:31]
	v_add_f32_e32 v245, v243, v244
	v_mov_b32_e32 v246, v245
	v_lshlrev_b32_e32 v247, 2, v32
	s_nop 0
	v_permlane32_swap_b32_e32 v246, v245
	v_add_f32_e32 v246, v246, v245
	s_mov_b64 exec, s[4:5]
	global_store_dword v247, v246, s[8:9] offset:256
	s_mov_b64 exec, -1
	v_mfma_f32_32x32x16_f16 v[0:15], v[82:85], v[174:177], 0
	v_mfma_f32_32x32x16_f16 v[0:15], v[86:89], v[170:173], v[0:15]
	v_mfma_f32_32x32x16_f16 v[0:15], v[90:93], v[166:169], v[0:15]
	s_nop 8
	v_max_i32_e32 v16, 0, v16
	v_max_i32_e32 v17, 0, v17
	v_fma_f32 v238, v16, v66, 0
	v_fma_f32 v239, v17, v67, 0
	v_max_i32_e32 v18, 0, v18
	v_max_i32_e32 v19, 0, v19
	v_fma_f32 v238, v18, v68, v238
	v_mfma_f32_32x32x16_f16 v[0:15], v[94:97], v[162:165], v[0:15]
	v_fma_f32 v239, v19, v69, v239
	v_max_i32_e32 v20, 0, v20
	v_max_i32_e32 v21, 0, v21
	v_fma_f32 v238, v20, v70, v238
	v_fma_f32 v239, v21, v71, v239
	v_max_i32_e32 v22, 0, v22
	v_max_i32_e32 v23, 0, v23
	v_mfma_f32_32x32x16_f16 v[0:15], v[98:101], v[158:161], v[0:15]
	v_fma_f32 v238, v22, v72, v238
	v_fma_f32 v239, v23, v73, v239
	v_max_i32_e32 v24, 0, v24
	v_max_i32_e32 v25, 0, v25
	v_fma_f32 v238, v24, v74, v238
	v_fma_f32 v239, v25, v75, v239
	v_mfma_f32_32x32x16_f16 v[0:15], v[102:105], v[154:157], v[0:15]
	v_max_i32_e32 v26, 0, v26
	v_max_i32_e32 v27, 0, v27
	v_fma_f32 v238, v26, v76, v238
	v_fma_f32 v239, v27, v77, v239
	v_max_i32_e32 v28, 0, v28
	v_max_i32_e32 v29, 0, v29
	v_mfma_f32_32x32x16_f16 v[0:15], v[106:109], v[150:153], v[0:15]
	v_fma_f32 v238, v28, v78, v238
	v_fma_f32 v239, v29, v79, v239
	v_max_i32_e32 v30, 0, v30
	v_max_i32_e32 v31, 0, v31
	v_fma_f32 v238, v30, v80, v238
	v_fma_f32 v239, v31, v81, v239
	v_mfma_f32_32x32x16_f16 v[0:15], v[110:113], v[146:149], v[0:15]
	v_add_f32_e32 v240, v238, v239
	v_mov_b32_e32 v241, v240
	v_lshlrev_b32_e32 v242, 2, v32
	s_nop 0
	v_permlane32_swap_b32_e32 v241, v240
	v_add_f32_e32 v241, v241, v240
	s_mov_b64 exec, s[4:5]
	global_store_dword v242, v241, s[6:7] offset:384
	s_mov_b64 exec, -1
	s_mov_b32 s98, 1
	s_andn2_b64 vcc, exec, s[10:11]
	s_cbranch_vccnz .LBB0_1888
	s_waitcnt vmcnt(7)
	ds_write_b128 v209, v[130:133]
	ds_write_b128 v209, v[138:141] offset:8704
	s_branch .LBB0_1888
